# prep_weights transposes: the 8 row loads (and 8 gain loads) of each half-item issued together with counted waits instead of one load per full wait
# speedup vs baseline: 1.0232x; 1.0045x over previous
; #define LAS __attribute__((address_space(3)))
; __device__ __forceinline__ unsigned pk2(float lo, float hi) { f32x2 v = {lo, hi}; bf16x2_t b = __builtin_convertvector(v, bf16x2_t); return __builtin_bit_cast(unsigned, b); }
;     if (ldk == 0) ldk = K;
;     const int c4 = lane & 15, kr = lane >> 4;
; #pragma unroll 8
;     for (int i = 0; i < 16; ++i) { const int kk = 4 * i + kr; const float gs = gain ? gain[k0 + kk] : 1.f; const f32x4 v = *(const f32x4*)(W + (size_t)(k0 + kk) * N + n0 + 4 * c4); *(LAS f32x4*)(scr + kk * 68 + 4 * c4) = v * gs; }
;     asm volatile("s_waitcnt lgkmcnt(0)" ::: "memory");
;     const int c = lane & 7;
; #pragma unroll
;     for (int j = 0; j < 8; ++j) { const int n = (lane >> 3) + 8 * j; const LAS float* s = scr + (8 * c) * 68 + n;
;         u32x4 o; o.x = pk2(s[0 * 68], s[1 * 68]); o.y = pk2(s[2 * 68], s[3 * 68]); o.z = pk2(s[4 * 68], s[5 * 68]); o.w = pk2(s[6 * 68], s[7 * 68]);
;         *(u32x4*)(WT + (size_t)(drow0 + n) * ldk + koff + k0 + 8 * c) = o; }
;     asm volatile("s_waitcnt lgkmcnt(0)" ::: "memory");
; }
;     const int nblk = N / 64, kb = item / nblk, nb = item % nblk;
;     transpose_item(W, N, K, WT, gain, nb * 64, kb * 64, nb * 64, scr, lane, ldk, koff);
.LBB0_336:
	v_lshl_add_u64 v[140:141], v[48:49], 0, s[78:79]
	global_load_dwordx4 v[140:143], v[140:141], off
	v_lshl_add_u64 v[144:145], v[46:47], 0, s[78:79]
	global_load_dwordx4 v[144:147], v[144:145], off
	v_lshl_add_u64 v[148:149], v[44:45], 0, s[78:79]
	global_load_dwordx4 v[148:151], v[148:149], off
	v_lshl_add_u64 v[152:153], v[42:43], 0, s[78:79]
	global_load_dwordx4 v[152:155], v[152:153], off
	v_lshl_add_u64 v[156:157], v[40:41], 0, s[78:79]
	global_load_dwordx4 v[156:159], v[156:157], off
	v_lshl_add_u64 v[160:161], v[38:39], 0, s[78:79]
	global_load_dwordx4 v[160:163], v[160:161], off
	v_lshl_add_u64 v[164:165], v[36:37], 0, s[78:79]
	global_load_dwordx4 v[164:167], v[164:165], off
	v_lshl_add_u64 v[168:169], v[34:35], 0, s[78:79]
	global_load_dwordx4 v[168:171], v[168:169], off
	s_add_u32 s78, s78, 0x20000
	s_addc_u32 s79, s79, 0
	v_lshl_add_u64 v[108:109], v[48:49], 0, s[78:79]
	global_load_dwordx4 v[108:111], v[108:109], off
	v_lshl_add_u64 v[112:113], v[46:47], 0, s[78:79]
	global_load_dwordx4 v[112:115], v[112:113], off
	v_lshl_add_u64 v[116:117], v[44:45], 0, s[78:79]
	global_load_dwordx4 v[116:119], v[116:117], off
	v_lshl_add_u64 v[120:121], v[42:43], 0, s[78:79]
	global_load_dwordx4 v[120:123], v[120:121], off
	v_lshl_add_u64 v[124:125], v[40:41], 0, s[78:79]
	global_load_dwordx4 v[124:127], v[124:125], off
	v_lshl_add_u64 v[240:241], v[38:39], 0, s[78:79]
	global_load_dwordx4 v[240:243], v[240:241], off
	v_lshl_add_u64 v[244:245], v[36:37], 0, s[78:79]
	global_load_dwordx4 v[244:247], v[244:245], off
	v_lshl_add_u64 v[248:249], v[34:35], 0, s[78:79]
	global_load_dwordx4 v[248:251], v[248:249], off
	s_add_u32 s78, s78, 0x20000
	s_addc_u32 s79, s79, 0
	s_waitcnt vmcnt(15)
	ds_write_b128 v33, v[140:143] offset:0
	s_waitcnt vmcnt(14)
	ds_write_b128 v33, v[144:147] offset:1088
	s_waitcnt vmcnt(13)
	ds_write_b128 v33, v[148:151] offset:2176
	s_waitcnt vmcnt(12)
	ds_write_b128 v33, v[152:155] offset:3264
	s_waitcnt vmcnt(11)
	ds_write_b128 v33, v[156:159] offset:4352
	s_waitcnt vmcnt(10)
	ds_write_b128 v33, v[160:163] offset:5440
	s_waitcnt vmcnt(9)
	ds_write_b128 v33, v[164:167] offset:6528
	s_waitcnt vmcnt(8)
	ds_write_b128 v33, v[168:171] offset:7616
	s_waitcnt vmcnt(7)
	ds_write_b128 v33, v[108:111] offset:8704
	s_waitcnt vmcnt(6)
	ds_write_b128 v33, v[112:115] offset:9792
	s_waitcnt vmcnt(5)
	ds_write_b128 v33, v[116:119] offset:10880
	s_waitcnt vmcnt(4)
	ds_write_b128 v33, v[120:123] offset:11968
	s_waitcnt vmcnt(3)
	ds_write_b128 v33, v[124:127] offset:13056
	s_waitcnt vmcnt(2)
	ds_write_b128 v33, v[240:243] offset:14144
	s_waitcnt vmcnt(1)
	ds_write_b128 v33, v[244:247] offset:15232
	s_waitcnt vmcnt(0)
	ds_write_b128 v33, v[248:251] offset:16320
	v_add_u32_e32 v33, 0x4400, v33
	s_cmp_lg_u32 s78, 0x40000
	s_waitcnt lgkmcnt(0)
	ds_read2_b32 v[40:41], v66 offset0:68 offset1:76
	ds_read2_b32 v[42:43], v66 offset1:8
	v_add_u32_e32 v58, 0x400, v66
	v_lshlrev_b16_e32 v33, 6, v1
	v_mov_b32_e32 v34, 0x39d00
	ds_read2_b32 v[44:45], v66 offset0:136 offset1:144
	ds_read2_b32 v[46:47], v66 offset0:204 offset1:212
	ds_read2_b32 v[48:49], v58 offset0:16 offset1:24
	ds_read2_b32 v[50:51], v58 offset0:84 offset1:92
	ds_read2_b32 v[52:53], v58 offset0:152 offset1:160
	ds_read2_b32 v[54:55], v58 offset0:220 offset1:228
	v_and_b32_e32 v33, 0x3c0, v33
	v_lshl_add_u32 v34, v1, 2, v34
	v_and_b32_e32 v34, 0x3ffc0, v34
	s_waitcnt lgkmcnt(6)
	v_cvt_pk_bf16_f32 v36, v42, v40
	v_or_b32_sdwa v40, v3, v33 dst_sel:DWORD dst_unused:UNUSED_PAD src0_sel:DWORD src1_sel:WORD_0
	v_lshlrev_b32_e32 v34, 1, v34
	v_mov_b32_e32 v35, v2
	v_mul_u32_u24_e32 v40, 0xb00, v40
	v_lshl_add_u64 v[34:35], v[4:5], 0, v[34:35]
	v_lshlrev_b32_e32 v56, 1, v40
	v_mov_b32_e32 v57, v2
	v_or_b32_sdwa v40, v67, v33 dst_sel:DWORD dst_unused:UNUSED_PAD src0_sel:DWORD src1_sel:WORD_0
	s_waitcnt lgkmcnt(4)
	v_cvt_pk_bf16_f32 v37, v44, v46
	s_waitcnt lgkmcnt(2)
	v_cvt_pk_bf16_f32 v38, v48, v50
	s_waitcnt lgkmcnt(0)
; #define LAS __attribute__((address_space(3)))
; __device__ __forceinline__ unsigned pk2(float lo, float hi) { f32x2 v = {lo, hi}; bf16x2_t b = __builtin_convertvector(v, bf16x2_t); return __builtin_bit_cast(unsigned, b); }
;     ...
;     const int c = lane & 7;
; #pragma unroll
;     for (int j = 0; j < 8; ++j) { const int n = (lane >> 3) + 8 * j; const LAS float* s = scr + (8 * c) * 68 + n;
;         u32x4 o; o.x = pk2(s[0 * 68], s[1 * 68]); o.y = pk2(s[2 * 68], s[3 * 68]); o.z = pk2(s[4 * 68], s[5 * 68]); o.w = pk2(s[6 * 68], s[7 * 68]);
;         *(u32x4*)(WT + (size_t)(drow0 + n) * ldk + koff + k0 + 8 * c) = o; }
;     asm volatile("s_waitcnt lgkmcnt(0)" ::: "memory");
; }
	v_cvt_pk_bf16_f32 v39, v52, v54
	v_lshl_add_u64 v[56:57], v[34:35], 0, v[56:57]
	v_mul_u32_u24_e32 v40, 0xb00, v40
	global_store_dwordx4 v[56:57], v[36:39], off
	v_lshlrev_b32_e32 v40, 1, v40
	v_mov_b32_e32 v57, v2
	v_cvt_pk_bf16_f32 v36, v43, v41
	v_mov_b32_e32 v41, v2
	v_cvt_pk_bf16_f32 v37, v45, v47
	v_cvt_pk_bf16_f32 v38, v49, v51
	v_cvt_pk_bf16_f32 v39, v53, v55
	v_lshl_add_u64 v[40:41], v[34:35], 0, v[40:41]
	global_store_dwordx4 v[40:41], v[36:39], off
	ds_read2_b32 v[40:41], v66 offset0:16 offset1:24
	ds_read2_b32 v[42:43], v66 offset0:84 offset1:92
	ds_read2_b32 v[44:45], v66 offset0:152 offset1:160
	ds_read2_b32 v[46:47], v66 offset0:220 offset1:228
	ds_read2_b32 v[48:49], v58 offset0:32 offset1:40
	ds_read2_b32 v[50:51], v58 offset0:100 offset1:108
	ds_read2_b32 v[52:53], v58 offset0:168 offset1:176
	ds_read2_b32 v[54:55], v58 offset0:236 offset1:244
	s_waitcnt lgkmcnt(6)
	v_cvt_pk_bf16_f32 v36, v40, v42
	v_or_b32_sdwa v40, v68, v33 dst_sel:DWORD dst_unused:UNUSED_PAD src0_sel:DWORD src1_sel:WORD_0
	v_mul_u32_u24_e32 v40, 0xb00, v40
	v_lshlrev_b32_e32 v56, 1, v40
	v_or_b32_sdwa v40, v69, v33 dst_sel:DWORD dst_unused:UNUSED_PAD src0_sel:DWORD src1_sel:WORD_0
	s_waitcnt lgkmcnt(4)
	v_cvt_pk_bf16_f32 v37, v44, v46
	s_waitcnt lgkmcnt(2)
	v_cvt_pk_bf16_f32 v38, v48, v50
	s_waitcnt lgkmcnt(0)
	v_cvt_pk_bf16_f32 v39, v52, v54
	v_lshl_add_u64 v[56:57], v[34:35], 0, v[56:57]
	v_mul_u32_u24_e32 v40, 0xb00, v40
	global_store_dwordx4 v[56:57], v[36:39], off
	v_lshlrev_b32_e32 v40, 1, v40
	v_mov_b32_e32 v57, v2
	v_cvt_pk_bf16_f32 v36, v41, v43
	v_mov_b32_e32 v41, v2
	v_cvt_pk_bf16_f32 v37, v45, v47
	v_cvt_pk_bf16_f32 v38, v49, v51
	v_cvt_pk_bf16_f32 v39, v53, v55
	v_lshl_add_u64 v[40:41], v[34:35], 0, v[40:41]
	global_store_dwordx4 v[40:41], v[36:39], off
	ds_read2_b32 v[40:41], v66 offset0:32 offset1:40
	ds_read2_b32 v[42:43], v66 offset0:100 offset1:108
	v_add_u32_e32 v39, 0x600, v66
	ds_read2_b32 v[44:45], v66 offset0:168 offset1:176
	ds_read2_b32 v[46:47], v66 offset0:236 offset1:244
	ds_read2_b32 v[48:49], v58 offset0:48 offset1:56
	ds_read2_b32 v[50:51], v58 offset0:116 offset1:124
	ds_read2_b32 v[52:53], v58 offset0:184 offset1:192
	ds_read2_b32 v[54:55], v39 offset0:124 offset1:132
	s_waitcnt lgkmcnt(6)
	v_cvt_pk_bf16_f32 v36, v40, v42
	v_or_b32_sdwa v40, v70, v33 dst_sel:DWORD dst_unused:UNUSED_PAD src0_sel:DWORD src1_sel:WORD_0
	v_mul_u32_u24_e32 v40, 0xb00, v40
	v_lshlrev_b32_e32 v56, 1, v40
	v_or_b32_sdwa v40, v71, v33 dst_sel:DWORD dst_unused:UNUSED_PAD src0_sel:DWORD src1_sel:WORD_0
	s_waitcnt lgkmcnt(4)
	v_cvt_pk_bf16_f32 v37, v44, v46
	s_waitcnt lgkmcnt(2)
	v_cvt_pk_bf16_f32 v38, v48, v50
	s_waitcnt lgkmcnt(0)
	v_cvt_pk_bf16_f32 v39, v52, v54
	v_lshl_add_u64 v[56:57], v[34:35], 0, v[56:57]
	v_mul_u32_u24_e32 v40, 0xb00, v40
	global_store_dwordx4 v[56:57], v[36:39], off
	v_lshlrev_b32_e32 v40, 1, v40
	v_mov_b32_e32 v57, v2
	v_cvt_pk_bf16_f32 v36, v41, v43
	v_mov_b32_e32 v41, v2
	v_cvt_pk_bf16_f32 v37, v45, v47
	v_cvt_pk_bf16_f32 v38, v49, v51
	v_cvt_pk_bf16_f32 v39, v53, v55
	v_lshl_add_u64 v[40:41], v[34:35], 0, v[40:41]
	global_store_dwordx4 v[40:41], v[36:39], off
	ds_read2_b32 v[40:41], v66 offset0:48 offset1:56
	ds_read2_b32 v[42:43], v66 offset0:116 offset1:124
	v_add_u32_e32 v37, 0x200, v66
	v_add_u32_e32 v39, 0x800, v66
	ds_read2_b32 v[44:45], v66 offset0:184 offset1:192
	ds_read2_b32 v[46:47], v37 offset0:124 offset1:132
	ds_read2_b32 v[48:49], v58 offset0:64 offset1:72
	ds_read2_b32 v[50:51], v58 offset0:132 offset1:140
	ds_read2_b32 v[52:53], v58 offset0:200 offset1:208
	ds_read2_b32 v[54:55], v39 offset0:12 offset1:20
	s_waitcnt lgkmcnt(6)
	v_cvt_pk_bf16_f32 v36, v40, v42
	v_or_b32_sdwa v40, v72, v33 dst_sel:DWORD dst_unused:UNUSED_PAD src0_sel:DWORD src1_sel:WORD_0
	v_mul_u32_u24_e32 v40, 0xb00, v40
	v_lshlrev_b32_e32 v56, 1, v40
	v_or_b32_sdwa v33, v73, v33 dst_sel:DWORD dst_unused:UNUSED_PAD src0_sel:DWORD src1_sel:WORD_0
	s_waitcnt lgkmcnt(4)
	v_cvt_pk_bf16_f32 v37, v44, v46
	s_waitcnt lgkmcnt(2)
	v_cvt_pk_bf16_f32 v38, v48, v50
	s_waitcnt lgkmcnt(0)
	v_cvt_pk_bf16_f32 v39, v52, v54
	v_lshl_add_u64 v[56:57], v[34:35], 0, v[56:57]
	v_mul_u32_u24_e32 v33, 0xb00, v33
	global_store_dwordx4 v[56:57], v[36:39], off
	v_lshlrev_b32_e32 v40, 1, v33
	s_nop 0
	v_cvt_pk_bf16_f32 v36, v41, v43
	v_mov_b32_e32 v41, v2
	v_cvt_pk_bf16_f32 v37, v45, v47
	v_cvt_pk_bf16_f32 v38, v49, v51
	v_cvt_pk_bf16_f32 v39, v53, v55
	v_lshl_add_u64 v[34:35], v[34:35], 0, v[40:41]
	global_store_dwordx4 v[34:35], v[36:39], off
	s_waitcnt lgkmcnt(0)

; #define LAS __attribute__((address_space(3)))
;     if (ldk == 0) ldk = K;
;     const int c4 = lane & 15, kr = lane >> 4;
; #pragma unroll 8
;     for (int i = 0; i < 16; ++i) { const int kk = 4 * i + kr; const float gs = gain ? gain[k0 + kk] : 1.f; const f32x4 v = *(const f32x4*)(W + (size_t)(k0 + kk) * N + n0 + 4 * c4); *(LAS f32x4*)(scr + kk * 68 + 4 * c4) = v * gs; }
;     asm volatile("s_waitcnt lgkmcnt(0)" ::: "memory");
; __device__ __forceinline__ void tr_gu(const float* W, bf16_t* WT, const float* gain, int up, int item, LAS float* scr, int lane) {
;     const int nblk = DFF / 64, kb = item / nblk, nb = item % nblk, n0 = nb * 64;
;     transpose_item(W, DFF, DM, WT, gain, (n0 >> 7) * 256 + (n0 & 127) + up * 128, kb * 64, n0, scr, lane);
; }
.LBB0_341:
	v_cndmask_b32_e64 v126, 0, 1, s[82:83]
	v_mov_b32_e32 v106, 1.0
	v_mov_b32_e32 v108, 1.0
	v_mov_b32_e32 v110, 1.0
	v_mov_b32_e32 v112, 1.0
	v_mov_b32_e32 v114, 1.0
	v_mov_b32_e32 v116, 1.0
	v_mov_b32_e32 v118, 1.0
	v_mov_b32_e32 v120, 1.0
	v_cmp_ne_u32_e64 s[40:41], 1, v126
	s_andn2_b64 vcc, exec, s[82:83]
	s_cbranch_vccnz .Lpw_ng_341
	v_lshl_add_u64 v[122:123], v[52:53], 0, s[46:47]
	global_load_dword v106, v[122:123], off
	v_lshl_add_u64 v[124:125], v[36:37], 0, s[46:47]
	global_load_dword v108, v[124:125], off offset:16
	global_load_dword v110, v[124:125], off offset:32
	global_load_dword v112, v[124:125], off offset:48
	global_load_dword v114, v[124:125], off offset:64
	global_load_dword v116, v[124:125], off offset:80
	global_load_dword v118, v[124:125], off offset:96
	global_load_dword v120, v[124:125], off offset:112
.Lpw_ng_341:
	v_lshl_add_u64 v[140:141], v[50:51], 0, s[80:81]
	global_load_dwordx4 v[140:143], v[140:141], off
	v_lshl_add_u64 v[144:145], v[48:49], 0, s[80:81]
	global_load_dwordx4 v[144:147], v[144:145], off
	v_lshl_add_u64 v[148:149], v[46:47], 0, s[80:81]
	global_load_dwordx4 v[148:151], v[148:149], off
	v_lshl_add_u64 v[152:153], v[44:45], 0, s[80:81]
	global_load_dwordx4 v[152:155], v[152:153], off
	v_lshl_add_u64 v[156:157], v[42:43], 0, s[80:81]
	global_load_dwordx4 v[156:159], v[156:157], off
	v_lshl_add_u64 v[160:161], v[40:41], 0, s[80:81]
	global_load_dwordx4 v[160:163], v[160:161], off
	v_lshl_add_u64 v[164:165], v[38:39], 0, s[80:81]
	global_load_dwordx4 v[164:167], v[164:165], off
	v_lshl_add_u64 v[168:169], v[34:35], 0, s[80:81]
	global_load_dwordx4 v[168:171], v[168:169], off
	s_add_u32 s80, s80, 0x58000
	s_addc_u32 s81, s81, 0
	v_lshl_add_u64 v[36:37], v[36:37], 0, s[34:35]
	v_lshl_add_u64 v[52:53], v[52:53], 0, s[34:35]
	s_waitcnt vmcnt(7)
	v_pk_mul_f32 v[140:141], v[140:141], v[106:107] op_sel_hi:[1,0]
	v_pk_mul_f32 v[142:143], v[142:143], v[106:107] op_sel_hi:[1,0]
	ds_write_b128 v60, v[140:143] offset:0
	s_waitcnt vmcnt(6)
	v_pk_mul_f32 v[144:145], v[144:145], v[108:109] op_sel_hi:[1,0]
	v_pk_mul_f32 v[146:147], v[146:147], v[108:109] op_sel_hi:[1,0]
	ds_write_b128 v60, v[144:147] offset:1088
	s_waitcnt vmcnt(5)
	v_pk_mul_f32 v[148:149], v[148:149], v[110:111] op_sel_hi:[1,0]
	v_pk_mul_f32 v[150:151], v[150:151], v[110:111] op_sel_hi:[1,0]
	ds_write_b128 v60, v[148:151] offset:2176
	s_waitcnt vmcnt(4)
	v_pk_mul_f32 v[152:153], v[152:153], v[112:113] op_sel_hi:[1,0]
	v_pk_mul_f32 v[154:155], v[154:155], v[112:113] op_sel_hi:[1,0]
	ds_write_b128 v60, v[152:155] offset:3264
	s_waitcnt vmcnt(3)
	v_pk_mul_f32 v[156:157], v[156:157], v[114:115] op_sel_hi:[1,0]
	v_pk_mul_f32 v[158:159], v[158:159], v[114:115] op_sel_hi:[1,0]
	ds_write_b128 v60, v[156:159] offset:4352
	s_waitcnt vmcnt(2)
	v_pk_mul_f32 v[160:161], v[160:161], v[116:117] op_sel_hi:[1,0]
	v_pk_mul_f32 v[162:163], v[162:163], v[116:117] op_sel_hi:[1,0]
	ds_write_b128 v60, v[160:163] offset:5440
	s_waitcnt vmcnt(1)
	v_pk_mul_f32 v[164:165], v[164:165], v[118:119] op_sel_hi:[1,0]
	v_pk_mul_f32 v[166:167], v[166:167], v[118:119] op_sel_hi:[1,0]
	ds_write_b128 v60, v[164:167] offset:6528
	s_waitcnt vmcnt(0)
	v_pk_mul_f32 v[168:169], v[168:169], v[120:121] op_sel_hi:[1,0]
	v_pk_mul_f32 v[170:171], v[170:171], v[120:121] op_sel_hi:[1,0]
	ds_write_b128 v60, v[168:171] offset:7616
	v_add_u32_e32 v60, 0x2200, v60
	s_cmp_lg_u32 s80, 0xb0000
	s_cbranch_scc1 .LBB0_341
	s_branch .LBB0_357

; #define LAS __attribute__((address_space(3)))
; __device__ __forceinline__ unsigned pk2(float lo, float hi) { f32x2 v = {lo, hi}; bf16x2_t b = __builtin_convertvector(v, bf16x2_t); return __builtin_bit_cast(unsigned, b); }
;     if (ldk == 0) ldk = K;
;     const int c4 = lane & 15, kr = lane >> 4;
; #pragma unroll 8
;     for (int i = 0; i < 16; ++i) { const int kk = 4 * i + kr; const float gs = gain ? gain[k0 + kk] : 1.f; const f32x4 v = *(const f32x4*)(W + (size_t)(k0 + kk) * N + n0 + 4 * c4); *(LAS f32x4*)(scr + kk * 68 + 4 * c4) = v * gs; }
;     asm volatile("s_waitcnt lgkmcnt(0)" ::: "memory");
;     const int c = lane & 7;
; #pragma unroll
;     for (int j = 0; j < 8; ++j) { const int n = (lane >> 3) + 8 * j; const LAS float* s = scr + (8 * c) * 68 + n;
;         u32x4 o; o.x = pk2(s[0 * 68], s[1 * 68]); o.y = pk2(s[2 * 68], s[3 * 68]); o.z = pk2(s[4 * 68], s[5 * 68]); o.w = pk2(s[6 * 68], s[7 * 68]);
;         *(u32x4*)(WT + (size_t)(drow0 + n) * ldk + koff + k0 + 8 * c) = o; }
;     asm volatile("s_waitcnt lgkmcnt(0)" ::: "memory");
; }
;     const int nblk = N / 64, kb = item / nblk, nb = item % nblk;
;     transpose_item(W, N, K, WT, gain, nb * 64, kb * 64, nb * 64, scr, lane, ldk, koff);
.LBB0_382:
	v_lshl_add_u64 v[140:141], v[48:49], 0, s[42:43]
	global_load_dwordx4 v[140:143], v[140:141], off
	v_lshl_add_u64 v[144:145], v[46:47], 0, s[42:43]
	global_load_dwordx4 v[144:147], v[144:145], off
	v_lshl_add_u64 v[148:149], v[44:45], 0, s[42:43]
	global_load_dwordx4 v[148:151], v[148:149], off
	v_lshl_add_u64 v[152:153], v[42:43], 0, s[42:43]
	global_load_dwordx4 v[152:155], v[152:153], off
	v_lshl_add_u64 v[156:157], v[40:41], 0, s[42:43]
	global_load_dwordx4 v[156:159], v[156:157], off
	v_lshl_add_u64 v[160:161], v[38:39], 0, s[42:43]
	global_load_dwordx4 v[160:163], v[160:161], off
	v_lshl_add_u64 v[164:165], v[36:37], 0, s[42:43]
	global_load_dwordx4 v[164:167], v[164:165], off
	v_lshl_add_u64 v[168:169], v[34:35], 0, s[42:43]
	global_load_dwordx4 v[168:171], v[168:169], off
	s_add_u32 s42, s42, 0x20000
	s_addc_u32 s43, s43, 0
	v_lshl_add_u64 v[108:109], v[48:49], 0, s[42:43]
	global_load_dwordx4 v[108:111], v[108:109], off
	v_lshl_add_u64 v[112:113], v[46:47], 0, s[42:43]
	global_load_dwordx4 v[112:115], v[112:113], off
	v_lshl_add_u64 v[116:117], v[44:45], 0, s[42:43]
	global_load_dwordx4 v[116:119], v[116:117], off
	v_lshl_add_u64 v[120:121], v[42:43], 0, s[42:43]
	global_load_dwordx4 v[120:123], v[120:121], off
	v_lshl_add_u64 v[124:125], v[40:41], 0, s[42:43]
	global_load_dwordx4 v[124:127], v[124:125], off
	v_lshl_add_u64 v[240:241], v[38:39], 0, s[42:43]
	global_load_dwordx4 v[240:243], v[240:241], off
	v_lshl_add_u64 v[244:245], v[36:37], 0, s[42:43]
	global_load_dwordx4 v[244:247], v[244:245], off
	v_lshl_add_u64 v[248:249], v[34:35], 0, s[42:43]
	global_load_dwordx4 v[248:251], v[248:249], off
	s_add_u32 s42, s42, 0x20000
	s_addc_u32 s43, s43, 0
	s_waitcnt vmcnt(15)
	ds_write_b128 v33, v[140:143] offset:0
	s_waitcnt vmcnt(14)
	ds_write_b128 v33, v[144:147] offset:1088
	s_waitcnt vmcnt(13)
	ds_write_b128 v33, v[148:151] offset:2176
	s_waitcnt vmcnt(12)
	ds_write_b128 v33, v[152:155] offset:3264
	s_waitcnt vmcnt(11)
	ds_write_b128 v33, v[156:159] offset:4352
	s_waitcnt vmcnt(10)
	ds_write_b128 v33, v[160:163] offset:5440
	s_waitcnt vmcnt(9)
	ds_write_b128 v33, v[164:167] offset:6528
	s_waitcnt vmcnt(8)
	ds_write_b128 v33, v[168:171] offset:7616
	s_waitcnt vmcnt(7)
	ds_write_b128 v33, v[108:111] offset:8704
	s_waitcnt vmcnt(6)
	ds_write_b128 v33, v[112:115] offset:9792
	s_waitcnt vmcnt(5)
	ds_write_b128 v33, v[116:119] offset:10880
	s_waitcnt vmcnt(4)
	ds_write_b128 v33, v[120:123] offset:11968
	s_waitcnt vmcnt(3)
	ds_write_b128 v33, v[124:127] offset:13056
	s_waitcnt vmcnt(2)
	ds_write_b128 v33, v[240:243] offset:14144
	s_waitcnt vmcnt(1)
	ds_write_b128 v33, v[244:247] offset:15232
	s_waitcnt vmcnt(0)
	ds_write_b128 v33, v[248:251] offset:16320
	v_add_u32_e32 v33, 0x4400, v33
	s_cmp_lg_u32 s42, 0x40000
	s_waitcnt lgkmcnt(0)
	ds_read2_b32 v[40:41], v66 offset0:68 offset1:76
	ds_read2_b32 v[42:43], v66 offset1:8
	v_add_u32_e32 v58, 0x400, v66
	v_mov_b32_e32 v34, 0x300
	ds_read2_b32 v[44:45], v66 offset0:136 offset1:144
	ds_read2_b32 v[46:47], v66 offset0:204 offset1:212
	ds_read2_b32 v[48:49], v58 offset0:16 offset1:24
	ds_read2_b32 v[50:51], v58 offset0:84 offset1:92
	ds_read2_b32 v[52:53], v58 offset0:152 offset1:160
	ds_read2_b32 v[54:55], v58 offset0:220 offset1:228
	v_and_b32_e32 v33, 15, v1
	v_lshl_add_u32 v34, v1, 2, v34
	v_and_b32_e32 v34, 0x3c0, v34
	v_lshlrev_b16_e32 v33, 6, v33
	v_lshlrev_b32_e32 v34, 1, v34
	v_mov_b32_e32 v35, v2
	s_waitcnt lgkmcnt(6)
	v_cvt_pk_bf16_f32 v36, v42, v40
	v_or_b32_e32 v40, v3, v33
	v_lshl_add_u64 v[34:35], v[8:9], 0, v[34:35]
	v_lshlrev_b32_e32 v56, 11, v40
	v_mov_b32_e32 v57, v2
	s_waitcnt lgkmcnt(4)
	v_cvt_pk_bf16_f32 v37, v44, v46
	s_waitcnt lgkmcnt(2)
	v_cvt_pk_bf16_f32 v38, v48, v50
	s_waitcnt lgkmcnt(0)
; #define LAS __attribute__((address_space(3)))
; __device__ __forceinline__ unsigned pk2(float lo, float hi) { f32x2 v = {lo, hi}; bf16x2_t b = __builtin_convertvector(v, bf16x2_t); return __builtin_bit_cast(unsigned, b); }
;     ...
;     const int c = lane & 7;
; #pragma unroll
;     for (int j = 0; j < 8; ++j) { const int n = (lane >> 3) + 8 * j; const LAS float* s = scr + (8 * c) * 68 + n;
;         u32x4 o; o.x = pk2(s[0 * 68], s[1 * 68]); o.y = pk2(s[2 * 68], s[3 * 68]); o.z = pk2(s[4 * 68], s[5 * 68]); o.w = pk2(s[6 * 68], s[7 * 68]);
;         *(u32x4*)(WT + (size_t)(drow0 + n) * ldk + koff + k0 + 8 * c) = o; }
;     asm volatile("s_waitcnt lgkmcnt(0)" ::: "memory");
; }
	v_cvt_pk_bf16_f32 v39, v52, v54
	v_lshl_add_u64 v[56:57], v[34:35], 0, v[56:57]
	v_or_b32_e32 v40, v67, v33
	global_store_dwordx4 v[56:57], v[36:39], off
	v_lshlrev_b32_e32 v40, 11, v40
	v_mov_b32_e32 v57, v2
	v_cvt_pk_bf16_f32 v36, v43, v41
	v_mov_b32_e32 v41, v2
	v_cvt_pk_bf16_f32 v37, v45, v47
	v_cvt_pk_bf16_f32 v38, v49, v51
	v_cvt_pk_bf16_f32 v39, v53, v55
	v_lshl_add_u64 v[40:41], v[34:35], 0, v[40:41]
	global_store_dwordx4 v[40:41], v[36:39], off
	ds_read2_b32 v[40:41], v66 offset0:84 offset1:92
	ds_read2_b32 v[42:43], v66 offset0:16 offset1:24
	ds_read2_b32 v[44:45], v66 offset0:152 offset1:160
	ds_read2_b32 v[46:47], v66 offset0:220 offset1:228
	ds_read2_b32 v[48:49], v58 offset0:32 offset1:40
	ds_read2_b32 v[50:51], v58 offset0:100 offset1:108
	ds_read2_b32 v[52:53], v58 offset0:168 offset1:176
	ds_read2_b32 v[54:55], v58 offset0:236 offset1:244
	s_waitcnt lgkmcnt(6)
	v_cvt_pk_bf16_f32 v36, v42, v40
	v_or_b32_e32 v40, v68, v33
	v_lshlrev_b32_e32 v56, 11, v40
	s_waitcnt lgkmcnt(4)
	v_cvt_pk_bf16_f32 v37, v44, v46
	s_waitcnt lgkmcnt(2)
	v_cvt_pk_bf16_f32 v38, v48, v50
	s_waitcnt lgkmcnt(0)
	v_cvt_pk_bf16_f32 v39, v52, v54
	v_lshl_add_u64 v[56:57], v[34:35], 0, v[56:57]
	v_or_b32_e32 v40, v69, v33
	global_store_dwordx4 v[56:57], v[36:39], off
	v_lshlrev_b32_e32 v40, 11, v40
	v_mov_b32_e32 v57, v2
	v_cvt_pk_bf16_f32 v36, v43, v41
	v_mov_b32_e32 v41, v2
	v_cvt_pk_bf16_f32 v37, v45, v47
	v_cvt_pk_bf16_f32 v38, v49, v51
	v_cvt_pk_bf16_f32 v39, v53, v55
	v_lshl_add_u64 v[40:41], v[34:35], 0, v[40:41]
	global_store_dwordx4 v[40:41], v[36:39], off
	ds_read2_b32 v[40:41], v66 offset0:32 offset1:40
	ds_read2_b32 v[42:43], v66 offset0:100 offset1:108
	v_add_u32_e32 v39, 0x600, v66
	ds_read2_b32 v[44:45], v66 offset0:168 offset1:176
	ds_read2_b32 v[46:47], v66 offset0:236 offset1:244
	ds_read2_b32 v[48:49], v58 offset0:48 offset1:56
	ds_read2_b32 v[50:51], v58 offset0:116 offset1:124
	ds_read2_b32 v[52:53], v58 offset0:184 offset1:192
	ds_read2_b32 v[54:55], v39 offset0:124 offset1:132
	s_waitcnt lgkmcnt(6)
	v_cvt_pk_bf16_f32 v36, v40, v42
	v_or_b32_e32 v40, v70, v33
	v_lshlrev_b32_e32 v56, 11, v40
	s_waitcnt lgkmcnt(4)
	v_cvt_pk_bf16_f32 v37, v44, v46
	s_waitcnt lgkmcnt(2)
	v_cvt_pk_bf16_f32 v38, v48, v50
	s_waitcnt lgkmcnt(0)
	v_cvt_pk_bf16_f32 v39, v52, v54
	v_lshl_add_u64 v[56:57], v[34:35], 0, v[56:57]
	v_or_b32_e32 v40, v71, v33
	global_store_dwordx4 v[56:57], v[36:39], off
	v_lshlrev_b32_e32 v40, 11, v40
	v_mov_b32_e32 v57, v2
	v_cvt_pk_bf16_f32 v36, v41, v43
	v_mov_b32_e32 v41, v2
	v_cvt_pk_bf16_f32 v37, v45, v47
	v_cvt_pk_bf16_f32 v38, v49, v51
	v_cvt_pk_bf16_f32 v39, v53, v55
	v_lshl_add_u64 v[40:41], v[34:35], 0, v[40:41]
	global_store_dwordx4 v[40:41], v[36:39], off
	ds_read2_b32 v[40:41], v66 offset0:48 offset1:56
	ds_read2_b32 v[42:43], v66 offset0:116 offset1:124
	v_add_u32_e32 v37, 0x200, v66
	v_add_u32_e32 v39, 0x800, v66
	ds_read2_b32 v[44:45], v66 offset0:184 offset1:192
	ds_read2_b32 v[46:47], v37 offset0:124 offset1:132
	ds_read2_b32 v[48:49], v58 offset0:64 offset1:72
	ds_read2_b32 v[50:51], v58 offset0:132 offset1:140
	ds_read2_b32 v[52:53], v58 offset0:200 offset1:208
	ds_read2_b32 v[54:55], v39 offset0:12 offset1:20
	s_waitcnt lgkmcnt(6)
	v_cvt_pk_bf16_f32 v36, v40, v42
	v_or_b32_e32 v40, v72, v33
	v_lshlrev_b32_e32 v56, 11, v40
	s_waitcnt lgkmcnt(4)
	v_cvt_pk_bf16_f32 v37, v44, v46
	s_waitcnt lgkmcnt(2)
	v_cvt_pk_bf16_f32 v38, v48, v50
	s_waitcnt lgkmcnt(0)
	v_cvt_pk_bf16_f32 v39, v52, v54
	v_lshl_add_u64 v[56:57], v[34:35], 0, v[56:57]
	v_or_b32_e32 v33, v73, v33
	global_store_dwordx4 v[56:57], v[36:39], off
	v_lshlrev_b32_e32 v40, 11, v33
	s_nop 0
	v_cvt_pk_bf16_f32 v36, v41, v43
	v_mov_b32_e32 v41, v2
	v_cvt_pk_bf16_f32 v37, v45, v47
	v_cvt_pk_bf16_f32 v38, v49, v51
	v_cvt_pk_bf16_f32 v39, v53, v55
	v_lshl_add_u64 v[34:35], v[34:35], 0, v[40:41]
	global_store_dwordx4 v[34:35], v[36:39], off
	s_waitcnt lgkmcnt(0)

; #define LAS __attribute__((address_space(3)))
; __device__ __forceinline__ unsigned pk2(float lo, float hi) { f32x2 v = {lo, hi}; bf16x2_t b = __builtin_convertvector(v, bf16x2_t); return __builtin_bit_cast(unsigned, b); }
;     if (ldk == 0) ldk = K;
;     const int c4 = lane & 15, kr = lane >> 4;
; #pragma unroll 8
;     for (int i = 0; i < 16; ++i) { const int kk = 4 * i + kr; const float gs = gain ? gain[k0 + kk] : 1.f; const f32x4 v = *(const f32x4*)(W + (size_t)(k0 + kk) * N + n0 + 4 * c4); *(LAS f32x4*)(scr + kk * 68 + 4 * c4) = v * gs; }
;     asm volatile("s_waitcnt lgkmcnt(0)" ::: "memory");
;     const int c = lane & 7;
; #pragma unroll
;     for (int j = 0; j < 8; ++j) { const int n = (lane >> 3) + 8 * j; const LAS float* s = scr + (8 * c) * 68 + n;
;         u32x4 o; o.x = pk2(s[0 * 68], s[1 * 68]); o.y = pk2(s[2 * 68], s[3 * 68]); o.z = pk2(s[4 * 68], s[5 * 68]); o.w = pk2(s[6 * 68], s[7 * 68]);
;         *(u32x4*)(WT + (size_t)(drow0 + n) * ldk + koff + k0 + 8 * c) = o; }
;     asm volatile("s_waitcnt lgkmcnt(0)" ::: "memory");
; }
;     const int nblk = N / 64, kb = item / nblk, nb = item % nblk;
;     transpose_item(W, N, K, WT, gain, nb * 64, kb * 64, nb * 64, scr, lane, ldk, koff);
.LBB0_387:
	v_lshl_add_u64 v[140:141], v[48:49], 0, s[42:43]
	global_load_dwordx4 v[140:143], v[140:141], off
	v_lshl_add_u64 v[144:145], v[46:47], 0, s[42:43]
	global_load_dwordx4 v[144:147], v[144:145], off
	v_lshl_add_u64 v[148:149], v[44:45], 0, s[42:43]
	global_load_dwordx4 v[148:151], v[148:149], off
	v_lshl_add_u64 v[152:153], v[42:43], 0, s[42:43]
	global_load_dwordx4 v[152:155], v[152:153], off
	v_lshl_add_u64 v[156:157], v[40:41], 0, s[42:43]
	global_load_dwordx4 v[156:159], v[156:157], off
	v_lshl_add_u64 v[160:161], v[38:39], 0, s[42:43]
	global_load_dwordx4 v[160:163], v[160:161], off
	v_lshl_add_u64 v[164:165], v[36:37], 0, s[42:43]
	global_load_dwordx4 v[164:167], v[164:165], off
	v_lshl_add_u64 v[168:169], v[34:35], 0, s[42:43]
	global_load_dwordx4 v[168:171], v[168:169], off
	s_add_u32 s42, s42, 0x20000
	s_addc_u32 s43, s43, 0
	v_lshl_add_u64 v[108:109], v[48:49], 0, s[42:43]
	global_load_dwordx4 v[108:111], v[108:109], off
	v_lshl_add_u64 v[112:113], v[46:47], 0, s[42:43]
	global_load_dwordx4 v[112:115], v[112:113], off
	v_lshl_add_u64 v[116:117], v[44:45], 0, s[42:43]
	global_load_dwordx4 v[116:119], v[116:117], off
	v_lshl_add_u64 v[120:121], v[42:43], 0, s[42:43]
	global_load_dwordx4 v[120:123], v[120:121], off
	v_lshl_add_u64 v[124:125], v[40:41], 0, s[42:43]
	global_load_dwordx4 v[124:127], v[124:125], off
	v_lshl_add_u64 v[240:241], v[38:39], 0, s[42:43]
	global_load_dwordx4 v[240:243], v[240:241], off
	v_lshl_add_u64 v[244:245], v[36:37], 0, s[42:43]
	global_load_dwordx4 v[244:247], v[244:245], off
	v_lshl_add_u64 v[248:249], v[34:35], 0, s[42:43]
	global_load_dwordx4 v[248:251], v[248:249], off
	s_add_u32 s42, s42, 0x20000
	s_addc_u32 s43, s43, 0
	s_waitcnt vmcnt(15)
	ds_write_b128 v33, v[140:143] offset:0
	s_waitcnt vmcnt(14)
	ds_write_b128 v33, v[144:147] offset:1088
	s_waitcnt vmcnt(13)
	ds_write_b128 v33, v[148:151] offset:2176
	s_waitcnt vmcnt(12)
	ds_write_b128 v33, v[152:155] offset:3264
	s_waitcnt vmcnt(11)
	ds_write_b128 v33, v[156:159] offset:4352
	s_waitcnt vmcnt(10)
	ds_write_b128 v33, v[160:163] offset:5440
	s_waitcnt vmcnt(9)
	ds_write_b128 v33, v[164:167] offset:6528
	s_waitcnt vmcnt(8)
	ds_write_b128 v33, v[168:171] offset:7616
	s_waitcnt vmcnt(7)
	ds_write_b128 v33, v[108:111] offset:8704
	s_waitcnt vmcnt(6)
	ds_write_b128 v33, v[112:115] offset:9792
	s_waitcnt vmcnt(5)
	ds_write_b128 v33, v[116:119] offset:10880
	s_waitcnt vmcnt(4)
	ds_write_b128 v33, v[120:123] offset:11968
	s_waitcnt vmcnt(3)
	ds_write_b128 v33, v[124:127] offset:13056
	s_waitcnt vmcnt(2)
	ds_write_b128 v33, v[240:243] offset:14144
	s_waitcnt vmcnt(1)
	ds_write_b128 v33, v[244:247] offset:15232
	s_waitcnt vmcnt(0)
	ds_write_b128 v33, v[248:251] offset:16320
	v_add_u32_e32 v33, 0x4400, v33
	s_cmp_lg_u32 s42, 0x40000
	s_waitcnt lgkmcnt(0)
	ds_read2_b32 v[40:41], v66 offset0:68 offset1:76
	ds_read2_b32 v[42:43], v66 offset1:8
	v_add_u32_e32 v58, 0x400, v66
	v_and_b32_e32 v33, 15, v1
	v_mov_b32_e32 v34, 0x100
	ds_read2_b32 v[44:45], v66 offset0:136 offset1:144
	ds_read2_b32 v[46:47], v66 offset0:204 offset1:212
	ds_read2_b32 v[48:49], v58 offset0:16 offset1:24
	ds_read2_b32 v[50:51], v58 offset0:84 offset1:92
	ds_read2_b32 v[52:53], v58 offset0:152 offset1:160
	ds_read2_b32 v[54:55], v58 offset0:220 offset1:228
	v_lshl_add_u32 v34, v1, 2, v34
	v_lshlrev_b16_e32 v33, 6, v33
	v_and_b32_e32 v34, 0x3c0, v34
	s_waitcnt lgkmcnt(6)
	v_cvt_pk_bf16_f32 v36, v42, v40
	v_or_b32_e32 v40, v3, v33
	v_lshlrev_b32_e32 v34, 1, v34
	v_mov_b32_e32 v35, v2
	v_mul_u32_u24_e32 v40, 0x600, v40
	v_lshl_add_u64 v[34:35], v[10:11], 0, v[34:35]
	v_lshlrev_b32_e32 v56, 1, v40
	v_mov_b32_e32 v57, v2
	v_or_b32_e32 v40, v67, v33
	s_waitcnt lgkmcnt(4)
	v_cvt_pk_bf16_f32 v37, v44, v46
	s_waitcnt lgkmcnt(2)
	v_cvt_pk_bf16_f32 v38, v48, v50
	s_waitcnt lgkmcnt(0)
; #define LAS __attribute__((address_space(3)))
; __device__ __forceinline__ unsigned pk2(float lo, float hi) { f32x2 v = {lo, hi}; bf16x2_t b = __builtin_convertvector(v, bf16x2_t); return __builtin_bit_cast(unsigned, b); }
;     ...
;     const int c = lane & 7;
; #pragma unroll
;     for (int j = 0; j < 8; ++j) { const int n = (lane >> 3) + 8 * j; const LAS float* s = scr + (8 * c) * 68 + n;
;         u32x4 o; o.x = pk2(s[0 * 68], s[1 * 68]); o.y = pk2(s[2 * 68], s[3 * 68]); o.z = pk2(s[4 * 68], s[5 * 68]); o.w = pk2(s[6 * 68], s[7 * 68]);
;         *(u32x4*)(WT + (size_t)(drow0 + n) * ldk + koff + k0 + 8 * c) = o; }
;     asm volatile("s_waitcnt lgkmcnt(0)" ::: "memory");
; }
	v_cvt_pk_bf16_f32 v39, v52, v54
	v_lshl_add_u64 v[56:57], v[34:35], 0, v[56:57]
	v_mul_u32_u24_e32 v40, 0x600, v40
	global_store_dwordx4 v[56:57], v[36:39], off
	v_lshlrev_b32_e32 v40, 1, v40
	v_mov_b32_e32 v57, v2
	v_cvt_pk_bf16_f32 v36, v43, v41
	v_mov_b32_e32 v41, v2
	v_cvt_pk_bf16_f32 v37, v45, v47
	v_cvt_pk_bf16_f32 v38, v49, v51
	v_cvt_pk_bf16_f32 v39, v53, v55
	v_lshl_add_u64 v[40:41], v[34:35], 0, v[40:41]
	global_store_dwordx4 v[40:41], v[36:39], off
	ds_read2_b32 v[40:41], v66 offset0:16 offset1:24
	ds_read2_b32 v[42:43], v66 offset0:84 offset1:92
	ds_read2_b32 v[44:45], v66 offset0:152 offset1:160
	ds_read2_b32 v[46:47], v66 offset0:220 offset1:228
	ds_read2_b32 v[48:49], v58 offset0:32 offset1:40
	ds_read2_b32 v[50:51], v58 offset0:100 offset1:108
	ds_read2_b32 v[52:53], v58 offset0:168 offset1:176
	ds_read2_b32 v[54:55], v58 offset0:236 offset1:244
	s_waitcnt lgkmcnt(6)
	v_cvt_pk_bf16_f32 v36, v40, v42
	v_or_b32_e32 v40, v68, v33
	v_mul_u32_u24_e32 v40, 0x600, v40
	v_lshlrev_b32_e32 v56, 1, v40
	v_or_b32_e32 v40, v69, v33
	s_waitcnt lgkmcnt(4)
	v_cvt_pk_bf16_f32 v37, v44, v46
	s_waitcnt lgkmcnt(2)
	v_cvt_pk_bf16_f32 v38, v48, v50
	s_waitcnt lgkmcnt(0)
	v_cvt_pk_bf16_f32 v39, v52, v54
	v_lshl_add_u64 v[56:57], v[34:35], 0, v[56:57]
	v_mul_u32_u24_e32 v40, 0x600, v40
	global_store_dwordx4 v[56:57], v[36:39], off
	v_lshlrev_b32_e32 v40, 1, v40
	v_mov_b32_e32 v57, v2
	v_cvt_pk_bf16_f32 v36, v41, v43
	v_mov_b32_e32 v41, v2
	v_cvt_pk_bf16_f32 v37, v45, v47
	v_cvt_pk_bf16_f32 v38, v49, v51
	v_cvt_pk_bf16_f32 v39, v53, v55
	v_lshl_add_u64 v[40:41], v[34:35], 0, v[40:41]
	global_store_dwordx4 v[40:41], v[36:39], off
	ds_read2_b32 v[40:41], v66 offset0:32 offset1:40
	ds_read2_b32 v[42:43], v66 offset0:100 offset1:108
	v_add_u32_e32 v39, 0x600, v66
	ds_read2_b32 v[44:45], v66 offset0:168 offset1:176
	ds_read2_b32 v[46:47], v66 offset0:236 offset1:244
	ds_read2_b32 v[48:49], v58 offset0:48 offset1:56
	ds_read2_b32 v[50:51], v58 offset0:116 offset1:124
	ds_read2_b32 v[52:53], v58 offset0:184 offset1:192
	ds_read2_b32 v[54:55], v39 offset0:124 offset1:132
	s_waitcnt lgkmcnt(6)
	v_cvt_pk_bf16_f32 v36, v40, v42
	v_or_b32_e32 v40, v70, v33
	v_mul_u32_u24_e32 v40, 0x600, v40
	v_lshlrev_b32_e32 v56, 1, v40
	v_or_b32_e32 v40, v71, v33
	s_waitcnt lgkmcnt(4)
	v_cvt_pk_bf16_f32 v37, v44, v46
	s_waitcnt lgkmcnt(2)
	v_cvt_pk_bf16_f32 v38, v48, v50
	s_waitcnt lgkmcnt(0)
	v_cvt_pk_bf16_f32 v39, v52, v54
	v_lshl_add_u64 v[56:57], v[34:35], 0, v[56:57]
	v_mul_u32_u24_e32 v40, 0x600, v40
	global_store_dwordx4 v[56:57], v[36:39], off
	v_lshlrev_b32_e32 v40, 1, v40
	v_mov_b32_e32 v57, v2
	v_cvt_pk_bf16_f32 v36, v41, v43
	v_mov_b32_e32 v41, v2
	v_cvt_pk_bf16_f32 v37, v45, v47
	v_cvt_pk_bf16_f32 v38, v49, v51
	v_cvt_pk_bf16_f32 v39, v53, v55
	v_lshl_add_u64 v[40:41], v[34:35], 0, v[40:41]
	global_store_dwordx4 v[40:41], v[36:39], off
	ds_read2_b32 v[40:41], v66 offset0:48 offset1:56
	ds_read2_b32 v[42:43], v66 offset0:116 offset1:124
	v_add_u32_e32 v37, 0x200, v66
	v_add_u32_e32 v39, 0x800, v66
	ds_read2_b32 v[44:45], v66 offset0:184 offset1:192
	ds_read2_b32 v[46:47], v37 offset0:124 offset1:132
	ds_read2_b32 v[48:49], v58 offset0:64 offset1:72
	ds_read2_b32 v[50:51], v58 offset0:132 offset1:140
	ds_read2_b32 v[52:53], v58 offset0:200 offset1:208
	ds_read2_b32 v[54:55], v39 offset0:12 offset1:20
	s_waitcnt lgkmcnt(6)
	v_cvt_pk_bf16_f32 v36, v40, v42
	v_or_b32_e32 v40, v72, v33
	v_mul_u32_u24_e32 v40, 0x600, v40
	v_lshlrev_b32_e32 v56, 1, v40
	v_or_b32_e32 v33, v73, v33
	s_waitcnt lgkmcnt(4)
	v_cvt_pk_bf16_f32 v37, v44, v46
	s_waitcnt lgkmcnt(2)
	v_cvt_pk_bf16_f32 v38, v48, v50
	s_waitcnt lgkmcnt(0)
	v_cvt_pk_bf16_f32 v39, v52, v54
	v_lshl_add_u64 v[56:57], v[34:35], 0, v[56:57]
	v_mul_u32_u24_e32 v33, 0x600, v33
	global_store_dwordx4 v[56:57], v[36:39], off
	v_lshlrev_b32_e32 v40, 1, v33
	s_nop 0
	v_cvt_pk_bf16_f32 v36, v41, v43
	v_mov_b32_e32 v41, v2
	v_cvt_pk_bf16_f32 v37, v45, v47
	v_cvt_pk_bf16_f32 v38, v49, v51
	v_cvt_pk_bf16_f32 v39, v53, v55
	v_lshl_add_u64 v[34:35], v[34:35], 0, v[40:41]
	global_store_dwordx4 v[34:35], v[36:39], off
	s_waitcnt lgkmcnt(0)

; #define LAS __attribute__((address_space(3)))
; __device__ __forceinline__ unsigned pk2(float lo, float hi) { f32x2 v = {lo, hi}; bf16x2_t b = __builtin_convertvector(v, bf16x2_t); return __builtin_bit_cast(unsigned, b); }
;     if (ldk == 0) ldk = K;
;     const int c4 = lane & 15, kr = lane >> 4;
; #pragma unroll 8
;     for (int i = 0; i < 16; ++i) { const int kk = 4 * i + kr; const float gs = gain ? gain[k0 + kk] : 1.f; const f32x4 v = *(const f32x4*)(W + (size_t)(k0 + kk) * N + n0 + 4 * c4); *(LAS f32x4*)(scr + kk * 68 + 4 * c4) = v * gs; }
;     asm volatile("s_waitcnt lgkmcnt(0)" ::: "memory");
;     const int c = lane & 7;
; #pragma unroll
;     for (int j = 0; j < 8; ++j) { const int n = (lane >> 3) + 8 * j; const LAS float* s = scr + (8 * c) * 68 + n;
;         u32x4 o; o.x = pk2(s[0 * 68], s[1 * 68]); o.y = pk2(s[2 * 68], s[3 * 68]); o.z = pk2(s[4 * 68], s[5 * 68]); o.w = pk2(s[6 * 68], s[7 * 68]);
;         *(u32x4*)(WT + (size_t)(drow0 + n) * ldk + koff + k0 + 8 * c) = o; }
;     asm volatile("s_waitcnt lgkmcnt(0)" ::: "memory");
; }
;     const int nblk = N / 64, kb = item / nblk, nb = item % nblk;
;     transpose_item(W, N, K, WT, gain, nb * 64, kb * 64, nb * 64, scr, lane, ldk, koff);
.LBB0_392:
	v_lshl_add_u64 v[140:141], v[48:49], 0, s[42:43]
	global_load_dwordx4 v[140:143], v[140:141], off
	v_lshl_add_u64 v[144:145], v[46:47], 0, s[42:43]
	global_load_dwordx4 v[144:147], v[144:145], off
	v_lshl_add_u64 v[148:149], v[44:45], 0, s[42:43]
	global_load_dwordx4 v[148:151], v[148:149], off
	v_lshl_add_u64 v[152:153], v[42:43], 0, s[42:43]
	global_load_dwordx4 v[152:155], v[152:153], off
	v_lshl_add_u64 v[156:157], v[40:41], 0, s[42:43]
	global_load_dwordx4 v[156:159], v[156:157], off
	v_lshl_add_u64 v[160:161], v[38:39], 0, s[42:43]
	global_load_dwordx4 v[160:163], v[160:161], off
	v_lshl_add_u64 v[164:165], v[36:37], 0, s[42:43]
	global_load_dwordx4 v[164:167], v[164:165], off
	v_lshl_add_u64 v[168:169], v[34:35], 0, s[42:43]
	global_load_dwordx4 v[168:171], v[168:169], off
	s_add_u32 s42, s42, 0x20000
	s_addc_u32 s43, s43, 0
	v_lshl_add_u64 v[108:109], v[48:49], 0, s[42:43]
	global_load_dwordx4 v[108:111], v[108:109], off
	v_lshl_add_u64 v[112:113], v[46:47], 0, s[42:43]
	global_load_dwordx4 v[112:115], v[112:113], off
	v_lshl_add_u64 v[116:117], v[44:45], 0, s[42:43]
	global_load_dwordx4 v[116:119], v[116:117], off
	v_lshl_add_u64 v[120:121], v[42:43], 0, s[42:43]
	global_load_dwordx4 v[120:123], v[120:121], off
	v_lshl_add_u64 v[124:125], v[40:41], 0, s[42:43]
	global_load_dwordx4 v[124:127], v[124:125], off
	v_lshl_add_u64 v[240:241], v[38:39], 0, s[42:43]
	global_load_dwordx4 v[240:243], v[240:241], off
	v_lshl_add_u64 v[244:245], v[36:37], 0, s[42:43]
	global_load_dwordx4 v[244:247], v[244:245], off
	v_lshl_add_u64 v[248:249], v[34:35], 0, s[42:43]
	global_load_dwordx4 v[248:251], v[248:249], off
	s_add_u32 s42, s42, 0x20000
	s_addc_u32 s43, s43, 0
	s_waitcnt vmcnt(15)
	ds_write_b128 v33, v[140:143] offset:0
	s_waitcnt vmcnt(14)
	ds_write_b128 v33, v[144:147] offset:1088
	s_waitcnt vmcnt(13)
	ds_write_b128 v33, v[148:151] offset:2176
	s_waitcnt vmcnt(12)
	ds_write_b128 v33, v[152:155] offset:3264
	s_waitcnt vmcnt(11)
	ds_write_b128 v33, v[156:159] offset:4352
	s_waitcnt vmcnt(10)
	ds_write_b128 v33, v[160:163] offset:5440
	s_waitcnt vmcnt(9)
	ds_write_b128 v33, v[164:167] offset:6528
	s_waitcnt vmcnt(8)
	ds_write_b128 v33, v[168:171] offset:7616
	s_waitcnt vmcnt(7)
	ds_write_b128 v33, v[108:111] offset:8704
	s_waitcnt vmcnt(6)
	ds_write_b128 v33, v[112:115] offset:9792
	s_waitcnt vmcnt(5)
	ds_write_b128 v33, v[116:119] offset:10880
	s_waitcnt vmcnt(4)
	ds_write_b128 v33, v[120:123] offset:11968
	s_waitcnt vmcnt(3)
	ds_write_b128 v33, v[124:127] offset:13056
	s_waitcnt vmcnt(2)
	ds_write_b128 v33, v[240:243] offset:14144
	s_waitcnt vmcnt(1)
	ds_write_b128 v33, v[244:247] offset:15232
	s_waitcnt vmcnt(0)
	ds_write_b128 v33, v[248:251] offset:16320
	v_add_u32_e32 v33, 0x4400, v33
	s_cmp_lg_u32 s42, 0x40000
	s_waitcnt lgkmcnt(0)
	ds_read2_b32 v[40:41], v66 offset0:68 offset1:76
	ds_read2_b32 v[42:43], v66 offset1:8
	v_add_u32_e32 v58, 0x400, v66
	v_and_b32_e32 v33, 15, v1
	v_mov_b32_e32 v34, 0x300
	ds_read2_b32 v[44:45], v66 offset0:136 offset1:144
	ds_read2_b32 v[46:47], v66 offset0:204 offset1:212
	ds_read2_b32 v[48:49], v58 offset0:16 offset1:24
	ds_read2_b32 v[50:51], v58 offset0:84 offset1:92
	ds_read2_b32 v[52:53], v58 offset0:152 offset1:160
	ds_read2_b32 v[54:55], v58 offset0:220 offset1:228
	v_lshl_add_u32 v34, v1, 2, v34
	v_lshlrev_b16_e32 v33, 6, v33
	v_and_b32_e32 v34, 0x3c0, v34
	s_waitcnt lgkmcnt(6)
	v_cvt_pk_bf16_f32 v36, v42, v40
	v_or_b32_e32 v40, v3, v33
	v_lshlrev_b32_e32 v34, 1, v34
	v_mov_b32_e32 v35, v2
	v_mul_u32_u24_e32 v40, 0x600, v40
	v_lshl_add_u64 v[34:35], v[12:13], 0, v[34:35]
	v_lshlrev_b32_e32 v56, 1, v40
	v_mov_b32_e32 v57, v2
	v_or_b32_e32 v40, v67, v33
	s_waitcnt lgkmcnt(4)
	v_cvt_pk_bf16_f32 v37, v44, v46
	s_waitcnt lgkmcnt(2)
	v_cvt_pk_bf16_f32 v38, v48, v50
	s_waitcnt lgkmcnt(0)
; #define LAS __attribute__((address_space(3)))
; __device__ __forceinline__ unsigned pk2(float lo, float hi) { f32x2 v = {lo, hi}; bf16x2_t b = __builtin_convertvector(v, bf16x2_t); return __builtin_bit_cast(unsigned, b); }
;     ...
;     const int c = lane & 7;
; #pragma unroll
;     for (int j = 0; j < 8; ++j) { const int n = (lane >> 3) + 8 * j; const LAS float* s = scr + (8 * c) * 68 + n;
;         u32x4 o; o.x = pk2(s[0 * 68], s[1 * 68]); o.y = pk2(s[2 * 68], s[3 * 68]); o.z = pk2(s[4 * 68], s[5 * 68]); o.w = pk2(s[6 * 68], s[7 * 68]);
;         *(u32x4*)(WT + (size_t)(drow0 + n) * ldk + koff + k0 + 8 * c) = o; }
;     asm volatile("s_waitcnt lgkmcnt(0)" ::: "memory");
; }
	v_cvt_pk_bf16_f32 v39, v52, v54
	v_lshl_add_u64 v[56:57], v[34:35], 0, v[56:57]
	v_mul_u32_u24_e32 v40, 0x600, v40
	global_store_dwordx4 v[56:57], v[36:39], off
	v_lshlrev_b32_e32 v40, 1, v40
	v_mov_b32_e32 v57, v2
	v_cvt_pk_bf16_f32 v36, v43, v41
	v_mov_b32_e32 v41, v2
	v_cvt_pk_bf16_f32 v37, v45, v47
	v_cvt_pk_bf16_f32 v38, v49, v51
	v_cvt_pk_bf16_f32 v39, v53, v55
	v_lshl_add_u64 v[40:41], v[34:35], 0, v[40:41]
	global_store_dwordx4 v[40:41], v[36:39], off
	ds_read2_b32 v[40:41], v66 offset0:16 offset1:24
	ds_read2_b32 v[42:43], v66 offset0:84 offset1:92
	ds_read2_b32 v[44:45], v66 offset0:152 offset1:160
	ds_read2_b32 v[46:47], v66 offset0:220 offset1:228
	ds_read2_b32 v[48:49], v58 offset0:32 offset1:40
	ds_read2_b32 v[50:51], v58 offset0:100 offset1:108
	ds_read2_b32 v[52:53], v58 offset0:168 offset1:176
	ds_read2_b32 v[54:55], v58 offset0:236 offset1:244
	s_waitcnt lgkmcnt(6)
	v_cvt_pk_bf16_f32 v36, v40, v42
	v_or_b32_e32 v40, v68, v33
	v_mul_u32_u24_e32 v40, 0x600, v40
	v_lshlrev_b32_e32 v56, 1, v40
	v_or_b32_e32 v40, v69, v33
	s_waitcnt lgkmcnt(4)
	v_cvt_pk_bf16_f32 v37, v44, v46
	s_waitcnt lgkmcnt(2)
	v_cvt_pk_bf16_f32 v38, v48, v50
	s_waitcnt lgkmcnt(0)
	v_cvt_pk_bf16_f32 v39, v52, v54
	v_lshl_add_u64 v[56:57], v[34:35], 0, v[56:57]
	v_mul_u32_u24_e32 v40, 0x600, v40
	global_store_dwordx4 v[56:57], v[36:39], off
	v_lshlrev_b32_e32 v40, 1, v40
	v_mov_b32_e32 v57, v2
	v_cvt_pk_bf16_f32 v36, v41, v43
	v_mov_b32_e32 v41, v2
	v_cvt_pk_bf16_f32 v37, v45, v47
	v_cvt_pk_bf16_f32 v38, v49, v51
	v_cvt_pk_bf16_f32 v39, v53, v55
	v_lshl_add_u64 v[40:41], v[34:35], 0, v[40:41]
	global_store_dwordx4 v[40:41], v[36:39], off
	ds_read2_b32 v[40:41], v66 offset0:32 offset1:40
	ds_read2_b32 v[42:43], v66 offset0:100 offset1:108
	v_add_u32_e32 v39, 0x600, v66
	ds_read2_b32 v[44:45], v66 offset0:168 offset1:176
	ds_read2_b32 v[46:47], v66 offset0:236 offset1:244
	ds_read2_b32 v[48:49], v58 offset0:48 offset1:56
	ds_read2_b32 v[50:51], v58 offset0:116 offset1:124
	ds_read2_b32 v[52:53], v58 offset0:184 offset1:192
	ds_read2_b32 v[54:55], v39 offset0:124 offset1:132
	s_waitcnt lgkmcnt(6)
	v_cvt_pk_bf16_f32 v36, v40, v42
	v_or_b32_e32 v40, v70, v33
	v_mul_u32_u24_e32 v40, 0x600, v40
	v_lshlrev_b32_e32 v56, 1, v40
	v_or_b32_e32 v40, v71, v33
	s_waitcnt lgkmcnt(4)
	v_cvt_pk_bf16_f32 v37, v44, v46
	s_waitcnt lgkmcnt(2)
	v_cvt_pk_bf16_f32 v38, v48, v50
	s_waitcnt lgkmcnt(0)
	v_cvt_pk_bf16_f32 v39, v52, v54
	v_lshl_add_u64 v[56:57], v[34:35], 0, v[56:57]
	v_mul_u32_u24_e32 v40, 0x600, v40
	global_store_dwordx4 v[56:57], v[36:39], off
	v_lshlrev_b32_e32 v40, 1, v40
	v_mov_b32_e32 v57, v2
	v_cvt_pk_bf16_f32 v36, v41, v43
	v_mov_b32_e32 v41, v2
	v_cvt_pk_bf16_f32 v37, v45, v47
	v_cvt_pk_bf16_f32 v38, v49, v51
	v_cvt_pk_bf16_f32 v39, v53, v55
	v_lshl_add_u64 v[40:41], v[34:35], 0, v[40:41]
	global_store_dwordx4 v[40:41], v[36:39], off
	ds_read2_b32 v[40:41], v66 offset0:48 offset1:56
	ds_read2_b32 v[42:43], v66 offset0:116 offset1:124
	v_add_u32_e32 v37, 0x200, v66
	v_add_u32_e32 v39, 0x800, v66
	ds_read2_b32 v[44:45], v66 offset0:184 offset1:192
	ds_read2_b32 v[46:47], v37 offset0:124 offset1:132
	ds_read2_b32 v[48:49], v58 offset0:64 offset1:72
	ds_read2_b32 v[50:51], v58 offset0:132 offset1:140
	ds_read2_b32 v[52:53], v58 offset0:200 offset1:208
	ds_read2_b32 v[54:55], v39 offset0:12 offset1:20
	s_waitcnt lgkmcnt(6)
	v_cvt_pk_bf16_f32 v36, v40, v42
	v_or_b32_e32 v40, v72, v33
	v_mul_u32_u24_e32 v40, 0x600, v40
	v_lshlrev_b32_e32 v56, 1, v40
	v_or_b32_e32 v33, v73, v33
	s_waitcnt lgkmcnt(4)
	v_cvt_pk_bf16_f32 v37, v44, v46
	s_waitcnt lgkmcnt(2)
	v_cvt_pk_bf16_f32 v38, v48, v50
	s_waitcnt lgkmcnt(0)
	v_cvt_pk_bf16_f32 v39, v52, v54
	v_lshl_add_u64 v[56:57], v[34:35], 0, v[56:57]
	v_mul_u32_u24_e32 v33, 0x600, v33
	global_store_dwordx4 v[56:57], v[36:39], off
	v_lshlrev_b32_e32 v40, 1, v33
	s_nop 0
	v_cvt_pk_bf16_f32 v36, v41, v43
	v_mov_b32_e32 v41, v2
	v_cvt_pk_bf16_f32 v37, v45, v47
	v_cvt_pk_bf16_f32 v38, v49, v51
	v_cvt_pk_bf16_f32 v39, v53, v55
	v_lshl_add_u64 v[34:35], v[34:35], 0, v[40:41]
	global_store_dwordx4 v[34:35], v[36:39], off
	s_waitcnt lgkmcnt(0)

; #define LAS __attribute__((address_space(3)))
; __device__ __forceinline__ unsigned pk2(float lo, float hi) { f32x2 v = {lo, hi}; bf16x2_t b = __builtin_convertvector(v, bf16x2_t); return __builtin_bit_cast(unsigned, b); }
;     if (ldk == 0) ldk = K;
;     const int c4 = lane & 15, kr = lane >> 4;
; #pragma unroll 8
;     for (int i = 0; i < 16; ++i) { const int kk = 4 * i + kr; const float gs = gain ? gain[k0 + kk] : 1.f; const f32x4 v = *(const f32x4*)(W + (size_t)(k0 + kk) * N + n0 + 4 * c4); *(LAS f32x4*)(scr + kk * 68 + 4 * c4) = v * gs; }
;     asm volatile("s_waitcnt lgkmcnt(0)" ::: "memory");
;     const int c = lane & 7;
; #pragma unroll
;     for (int j = 0; j < 8; ++j) { const int n = (lane >> 3) + 8 * j; const LAS float* s = scr + (8 * c) * 68 + n;
;         u32x4 o; o.x = pk2(s[0 * 68], s[1 * 68]); o.y = pk2(s[2 * 68], s[3 * 68]); o.z = pk2(s[4 * 68], s[5 * 68]); o.w = pk2(s[6 * 68], s[7 * 68]);
;         *(u32x4*)(WT + (size_t)(drow0 + n) * ldk + koff + k0 + 8 * c) = o; }
;     asm volatile("s_waitcnt lgkmcnt(0)" ::: "memory");
; }
;     const int nblk = N / 64, kb = item / nblk, nb = item % nblk;
;     transpose_item(W, N, K, WT, gain, nb * 64, kb * 64, nb * 64, scr, lane, ldk, koff);
.LBB0_397:
	v_lshl_add_u64 v[140:141], v[48:49], 0, s[42:43]
	global_load_dwordx4 v[140:143], v[140:141], off
	v_lshl_add_u64 v[144:145], v[46:47], 0, s[42:43]
	global_load_dwordx4 v[144:147], v[144:145], off
	v_lshl_add_u64 v[148:149], v[44:45], 0, s[42:43]
	global_load_dwordx4 v[148:151], v[148:149], off
	v_lshl_add_u64 v[152:153], v[42:43], 0, s[42:43]
	global_load_dwordx4 v[152:155], v[152:153], off
	v_lshl_add_u64 v[156:157], v[40:41], 0, s[42:43]
	global_load_dwordx4 v[156:159], v[156:157], off
	v_lshl_add_u64 v[160:161], v[38:39], 0, s[42:43]
	global_load_dwordx4 v[160:163], v[160:161], off
	v_lshl_add_u64 v[164:165], v[36:37], 0, s[42:43]
	global_load_dwordx4 v[164:167], v[164:165], off
	v_lshl_add_u64 v[168:169], v[34:35], 0, s[42:43]
	global_load_dwordx4 v[168:171], v[168:169], off
	s_add_u32 s42, s42, 0x20000
	s_addc_u32 s43, s43, 0
	v_lshl_add_u64 v[108:109], v[48:49], 0, s[42:43]
	global_load_dwordx4 v[108:111], v[108:109], off
	v_lshl_add_u64 v[112:113], v[46:47], 0, s[42:43]
	global_load_dwordx4 v[112:115], v[112:113], off
	v_lshl_add_u64 v[116:117], v[44:45], 0, s[42:43]
	global_load_dwordx4 v[116:119], v[116:117], off
	v_lshl_add_u64 v[120:121], v[42:43], 0, s[42:43]
	global_load_dwordx4 v[120:123], v[120:121], off
	v_lshl_add_u64 v[124:125], v[40:41], 0, s[42:43]
	global_load_dwordx4 v[124:127], v[124:125], off
	v_lshl_add_u64 v[240:241], v[38:39], 0, s[42:43]
	global_load_dwordx4 v[240:243], v[240:241], off
	v_lshl_add_u64 v[244:245], v[36:37], 0, s[42:43]
	global_load_dwordx4 v[244:247], v[244:245], off
	v_lshl_add_u64 v[248:249], v[34:35], 0, s[42:43]
	global_load_dwordx4 v[248:251], v[248:249], off
	s_add_u32 s42, s42, 0x20000
	s_addc_u32 s43, s43, 0
	s_waitcnt vmcnt(15)
	ds_write_b128 v33, v[140:143] offset:0
	s_waitcnt vmcnt(14)
	ds_write_b128 v33, v[144:147] offset:1088
	s_waitcnt vmcnt(13)
	ds_write_b128 v33, v[148:151] offset:2176
	s_waitcnt vmcnt(12)
	ds_write_b128 v33, v[152:155] offset:3264
	s_waitcnt vmcnt(11)
	ds_write_b128 v33, v[156:159] offset:4352
	s_waitcnt vmcnt(10)
	ds_write_b128 v33, v[160:163] offset:5440
	s_waitcnt vmcnt(9)
	ds_write_b128 v33, v[164:167] offset:6528
	s_waitcnt vmcnt(8)
	ds_write_b128 v33, v[168:171] offset:7616
	s_waitcnt vmcnt(7)
	ds_write_b128 v33, v[108:111] offset:8704
	s_waitcnt vmcnt(6)
	ds_write_b128 v33, v[112:115] offset:9792
	s_waitcnt vmcnt(5)
	ds_write_b128 v33, v[116:119] offset:10880
	s_waitcnt vmcnt(4)
	ds_write_b128 v33, v[120:123] offset:11968
	s_waitcnt vmcnt(3)
	ds_write_b128 v33, v[124:127] offset:13056
	s_waitcnt vmcnt(2)
	ds_write_b128 v33, v[240:243] offset:14144
	s_waitcnt vmcnt(1)
	ds_write_b128 v33, v[244:247] offset:15232
	s_waitcnt vmcnt(0)
	ds_write_b128 v33, v[248:251] offset:16320
	v_add_u32_e32 v33, 0x4400, v33
	s_cmp_lg_u32 s42, 0x40000
	s_waitcnt lgkmcnt(0)
	ds_read2_b32 v[40:41], v66 offset0:68 offset1:76
	ds_read2_b32 v[42:43], v66 offset1:8
	v_add_u32_e32 v58, 0x400, v66
	v_and_b32_e32 v33, 15, v1
	v_mov_b32_e32 v34, 0x100
	ds_read2_b32 v[44:45], v66 offset0:136 offset1:144
	ds_read2_b32 v[46:47], v66 offset0:204 offset1:212
	ds_read2_b32 v[48:49], v58 offset0:16 offset1:24
	ds_read2_b32 v[50:51], v58 offset0:84 offset1:92
	ds_read2_b32 v[52:53], v58 offset0:152 offset1:160
	ds_read2_b32 v[54:55], v58 offset0:220 offset1:228
	v_lshl_add_u32 v34, v1, 2, v34
	v_lshlrev_b16_e32 v33, 6, v33
	v_and_b32_e32 v34, 0x3c0, v34
	s_waitcnt lgkmcnt(6)
	v_cvt_pk_bf16_f32 v36, v42, v40
	v_or_b32_e32 v40, v3, v33
	v_lshlrev_b32_e32 v34, 1, v34
	v_mov_b32_e32 v35, v2
	v_mul_u32_u24_e32 v40, 0x600, v40
	v_lshl_add_u64 v[34:35], v[14:15], 0, v[34:35]
	v_lshlrev_b32_e32 v56, 1, v40
	v_mov_b32_e32 v57, v2
	v_or_b32_e32 v40, v67, v33
	s_waitcnt lgkmcnt(4)
	v_cvt_pk_bf16_f32 v37, v44, v46
	s_waitcnt lgkmcnt(2)
	v_cvt_pk_bf16_f32 v38, v48, v50
	s_waitcnt lgkmcnt(0)
; #define LAS __attribute__((address_space(3)))
; __device__ __forceinline__ unsigned pk2(float lo, float hi) { f32x2 v = {lo, hi}; bf16x2_t b = __builtin_convertvector(v, bf16x2_t); return __builtin_bit_cast(unsigned, b); }
;     ...
;     const int c = lane & 7;
; #pragma unroll
;     for (int j = 0; j < 8; ++j) { const int n = (lane >> 3) + 8 * j; const LAS float* s = scr + (8 * c) * 68 + n;
;         u32x4 o; o.x = pk2(s[0 * 68], s[1 * 68]); o.y = pk2(s[2 * 68], s[3 * 68]); o.z = pk2(s[4 * 68], s[5 * 68]); o.w = pk2(s[6 * 68], s[7 * 68]);
;         *(u32x4*)(WT + (size_t)(drow0 + n) * ldk + koff + k0 + 8 * c) = o; }
;     asm volatile("s_waitcnt lgkmcnt(0)" ::: "memory");
; }
	v_cvt_pk_bf16_f32 v39, v52, v54
	v_lshl_add_u64 v[56:57], v[34:35], 0, v[56:57]
	v_mul_u32_u24_e32 v40, 0x600, v40
	global_store_dwordx4 v[56:57], v[36:39], off
	v_lshlrev_b32_e32 v40, 1, v40
	v_mov_b32_e32 v57, v2
	v_cvt_pk_bf16_f32 v36, v43, v41
	v_mov_b32_e32 v41, v2
	v_cvt_pk_bf16_f32 v37, v45, v47
	v_cvt_pk_bf16_f32 v38, v49, v51
	v_cvt_pk_bf16_f32 v39, v53, v55
	v_lshl_add_u64 v[40:41], v[34:35], 0, v[40:41]
	global_store_dwordx4 v[40:41], v[36:39], off
	ds_read2_b32 v[40:41], v66 offset0:16 offset1:24
	ds_read2_b32 v[42:43], v66 offset0:84 offset1:92
	ds_read2_b32 v[44:45], v66 offset0:152 offset1:160
	ds_read2_b32 v[46:47], v66 offset0:220 offset1:228
	ds_read2_b32 v[48:49], v58 offset0:32 offset1:40
	ds_read2_b32 v[50:51], v58 offset0:100 offset1:108
	ds_read2_b32 v[52:53], v58 offset0:168 offset1:176
	ds_read2_b32 v[54:55], v58 offset0:236 offset1:244
	s_waitcnt lgkmcnt(6)
	v_cvt_pk_bf16_f32 v36, v40, v42
	v_or_b32_e32 v40, v68, v33
	v_mul_u32_u24_e32 v40, 0x600, v40
	v_lshlrev_b32_e32 v56, 1, v40
	v_or_b32_e32 v40, v69, v33
	s_waitcnt lgkmcnt(4)
	v_cvt_pk_bf16_f32 v37, v44, v46
	s_waitcnt lgkmcnt(2)
	v_cvt_pk_bf16_f32 v38, v48, v50
	s_waitcnt lgkmcnt(0)
	v_cvt_pk_bf16_f32 v39, v52, v54
	v_lshl_add_u64 v[56:57], v[34:35], 0, v[56:57]
	v_mul_u32_u24_e32 v40, 0x600, v40
	global_store_dwordx4 v[56:57], v[36:39], off
	v_lshlrev_b32_e32 v40, 1, v40
	v_mov_b32_e32 v57, v2
	v_cvt_pk_bf16_f32 v36, v41, v43
	v_mov_b32_e32 v41, v2
	v_cvt_pk_bf16_f32 v37, v45, v47
	v_cvt_pk_bf16_f32 v38, v49, v51
	v_cvt_pk_bf16_f32 v39, v53, v55
	v_lshl_add_u64 v[40:41], v[34:35], 0, v[40:41]
	global_store_dwordx4 v[40:41], v[36:39], off
	ds_read2_b32 v[40:41], v66 offset0:32 offset1:40
	ds_read2_b32 v[42:43], v66 offset0:100 offset1:108
	v_add_u32_e32 v39, 0x600, v66
	ds_read2_b32 v[44:45], v66 offset0:168 offset1:176
	ds_read2_b32 v[46:47], v66 offset0:236 offset1:244
	ds_read2_b32 v[48:49], v58 offset0:48 offset1:56
	ds_read2_b32 v[50:51], v58 offset0:116 offset1:124
	ds_read2_b32 v[52:53], v58 offset0:184 offset1:192
	ds_read2_b32 v[54:55], v39 offset0:124 offset1:132
	s_waitcnt lgkmcnt(6)
	v_cvt_pk_bf16_f32 v36, v40, v42
	v_or_b32_e32 v40, v70, v33
	v_mul_u32_u24_e32 v40, 0x600, v40
	v_lshlrev_b32_e32 v56, 1, v40
	v_or_b32_e32 v40, v71, v33
	s_waitcnt lgkmcnt(4)
	v_cvt_pk_bf16_f32 v37, v44, v46
	s_waitcnt lgkmcnt(2)
	v_cvt_pk_bf16_f32 v38, v48, v50
	s_waitcnt lgkmcnt(0)
	v_cvt_pk_bf16_f32 v39, v52, v54
	v_lshl_add_u64 v[56:57], v[34:35], 0, v[56:57]
	v_mul_u32_u24_e32 v40, 0x600, v40
	global_store_dwordx4 v[56:57], v[36:39], off
	v_lshlrev_b32_e32 v40, 1, v40
	v_mov_b32_e32 v57, v2
	v_cvt_pk_bf16_f32 v36, v41, v43
	v_mov_b32_e32 v41, v2
	v_cvt_pk_bf16_f32 v37, v45, v47
	v_cvt_pk_bf16_f32 v38, v49, v51
	v_cvt_pk_bf16_f32 v39, v53, v55
	v_lshl_add_u64 v[40:41], v[34:35], 0, v[40:41]
	global_store_dwordx4 v[40:41], v[36:39], off
	ds_read2_b32 v[40:41], v66 offset0:48 offset1:56
	ds_read2_b32 v[42:43], v66 offset0:116 offset1:124
	v_add_u32_e32 v37, 0x200, v66
	v_add_u32_e32 v39, 0x800, v66
	ds_read2_b32 v[44:45], v66 offset0:184 offset1:192
	ds_read2_b32 v[46:47], v37 offset0:124 offset1:132
	ds_read2_b32 v[48:49], v58 offset0:64 offset1:72
	ds_read2_b32 v[50:51], v58 offset0:132 offset1:140
	ds_read2_b32 v[52:53], v58 offset0:200 offset1:208
	ds_read2_b32 v[54:55], v39 offset0:12 offset1:20
	s_waitcnt lgkmcnt(6)
	v_cvt_pk_bf16_f32 v36, v40, v42
	v_or_b32_e32 v40, v72, v33
	v_mul_u32_u24_e32 v40, 0x600, v40
	v_lshlrev_b32_e32 v56, 1, v40
	v_or_b32_e32 v33, v73, v33
	s_waitcnt lgkmcnt(4)
	v_cvt_pk_bf16_f32 v37, v44, v46
	s_waitcnt lgkmcnt(2)
	v_cvt_pk_bf16_f32 v38, v48, v50
	s_waitcnt lgkmcnt(0)
	v_cvt_pk_bf16_f32 v39, v52, v54
	v_lshl_add_u64 v[56:57], v[34:35], 0, v[56:57]
	v_mul_u32_u24_e32 v33, 0x600, v33
	global_store_dwordx4 v[56:57], v[36:39], off
	v_lshlrev_b32_e32 v40, 1, v33
	s_nop 0
	v_cvt_pk_bf16_f32 v36, v41, v43
	v_mov_b32_e32 v41, v2
	v_cvt_pk_bf16_f32 v37, v45, v47
	v_cvt_pk_bf16_f32 v38, v49, v51
	v_cvt_pk_bf16_f32 v39, v53, v55
	v_lshl_add_u64 v[34:35], v[34:35], 0, v[40:41]
	global_store_dwordx4 v[34:35], v[36:39], off
	s_waitcnt lgkmcnt(0)

; #define LAS __attribute__((address_space(3)))
;     if (ldk == 0) ldk = K;
;     const int c4 = lane & 15, kr = lane >> 4;
; #pragma unroll 8
;     for (int i = 0; i < 16; ++i) { const int kk = 4 * i + kr; const float gs = gain ? gain[k0 + kk] : 1.f; const f32x4 v = *(const f32x4*)(W + (size_t)(k0 + kk) * N + n0 + 4 * c4); *(LAS f32x4*)(scr + kk * 68 + 4 * c4) = v * gs; }
;     asm volatile("s_waitcnt lgkmcnt(0)" ::: "memory");
;     const int nblk = N / 64, kb = item / nblk, nb = item % nblk;
;     transpose_item(W, N, K, WT, gain, nb * 64, kb * 64, nb * 64, scr, lane, ldk, koff);
; }
.LBB0_403:
	v_cndmask_b32_e64 v126, 0, 1, s[72:73]
	v_mov_b32_e32 v106, 1.0
	v_mov_b32_e32 v108, 1.0
	v_mov_b32_e32 v110, 1.0
	v_mov_b32_e32 v112, 1.0
	v_mov_b32_e32 v114, 1.0
	v_mov_b32_e32 v116, 1.0
	v_mov_b32_e32 v118, 1.0
	v_mov_b32_e32 v120, 1.0
	v_cmp_ne_u32_e64 s[40:41], 1, v126
	s_andn2_b64 vcc, exec, s[72:73]
	s_cbranch_vccnz .Lpw_ng_403
	v_lshl_add_u64 v[122:123], v[52:53], 0, s[46:47]
	global_load_dword v106, v[122:123], off
	v_lshl_add_u64 v[124:125], v[36:37], 0, s[46:47]
	global_load_dword v108, v[124:125], off offset:16
	global_load_dword v110, v[124:125], off offset:32
	global_load_dword v112, v[124:125], off offset:48
	global_load_dword v114, v[124:125], off offset:64
	global_load_dword v116, v[124:125], off offset:80
	global_load_dword v118, v[124:125], off offset:96
	global_load_dword v120, v[124:125], off offset:112
.Lpw_ng_403:
	v_lshl_add_u64 v[140:141], v[50:51], 0, s[70:71]
	global_load_dwordx4 v[140:143], v[140:141], off
	v_lshl_add_u64 v[144:145], v[48:49], 0, s[70:71]
	global_load_dwordx4 v[144:147], v[144:145], off
	v_lshl_add_u64 v[148:149], v[46:47], 0, s[70:71]
	global_load_dwordx4 v[148:151], v[148:149], off
	v_lshl_add_u64 v[152:153], v[44:45], 0, s[70:71]
	global_load_dwordx4 v[152:155], v[152:153], off
	v_lshl_add_u64 v[156:157], v[42:43], 0, s[70:71]
	global_load_dwordx4 v[156:159], v[156:157], off
	v_lshl_add_u64 v[160:161], v[40:41], 0, s[70:71]
	global_load_dwordx4 v[160:163], v[160:161], off
	v_lshl_add_u64 v[164:165], v[38:39], 0, s[70:71]
	global_load_dwordx4 v[164:167], v[164:165], off
	v_lshl_add_u64 v[168:169], v[34:35], 0, s[70:71]
	global_load_dwordx4 v[168:171], v[168:169], off
	s_add_u32 s70, s70, 0x110000
	s_addc_u32 s71, s71, 0
	v_lshl_add_u64 v[36:37], v[36:37], 0, s[34:35]
	v_lshl_add_u64 v[52:53], v[52:53], 0, s[34:35]
	s_waitcnt vmcnt(7)
	v_pk_mul_f32 v[140:141], v[140:141], v[106:107] op_sel_hi:[1,0]
	v_pk_mul_f32 v[142:143], v[142:143], v[106:107] op_sel_hi:[1,0]
	ds_write_b128 v59, v[140:143] offset:0
	s_waitcnt vmcnt(6)
	v_pk_mul_f32 v[144:145], v[144:145], v[108:109] op_sel_hi:[1,0]
	v_pk_mul_f32 v[146:147], v[146:147], v[108:109] op_sel_hi:[1,0]
	ds_write_b128 v59, v[144:147] offset:1088
	s_waitcnt vmcnt(5)
	v_pk_mul_f32 v[148:149], v[148:149], v[110:111] op_sel_hi:[1,0]
	v_pk_mul_f32 v[150:151], v[150:151], v[110:111] op_sel_hi:[1,0]
	ds_write_b128 v59, v[148:151] offset:2176
	s_waitcnt vmcnt(4)
	v_pk_mul_f32 v[152:153], v[152:153], v[112:113] op_sel_hi:[1,0]
	v_pk_mul_f32 v[154:155], v[154:155], v[112:113] op_sel_hi:[1,0]
	ds_write_b128 v59, v[152:155] offset:3264
	s_waitcnt vmcnt(3)
	v_pk_mul_f32 v[156:157], v[156:157], v[114:115] op_sel_hi:[1,0]
	v_pk_mul_f32 v[158:159], v[158:159], v[114:115] op_sel_hi:[1,0]
	ds_write_b128 v59, v[156:159] offset:4352
	s_waitcnt vmcnt(2)
	v_pk_mul_f32 v[160:161], v[160:161], v[116:117] op_sel_hi:[1,0]
	v_pk_mul_f32 v[162:163], v[162:163], v[116:117] op_sel_hi:[1,0]
	ds_write_b128 v59, v[160:163] offset:5440
	s_waitcnt vmcnt(1)
	v_pk_mul_f32 v[164:165], v[164:165], v[118:119] op_sel_hi:[1,0]
	v_pk_mul_f32 v[166:167], v[166:167], v[118:119] op_sel_hi:[1,0]
	ds_write_b128 v59, v[164:167] offset:6528
	s_waitcnt vmcnt(0)
	v_pk_mul_f32 v[168:169], v[168:169], v[120:121] op_sel_hi:[1,0]
	v_pk_mul_f32 v[170:171], v[170:171], v[120:121] op_sel_hi:[1,0]
	ds_write_b128 v59, v[168:171] offset:7616
	v_add_u32_e32 v59, 0x2200, v59
	s_cmp_lg_u32 s70, 0x220000
	s_cbranch_scc1 .LBB0_403
	s_branch .LBB0_419

; #define LAS __attribute__((address_space(3)))
; __device__ __forceinline__ unsigned pk2(float lo, float hi) { f32x2 v = {lo, hi}; bf16x2_t b = __builtin_convertvector(v, bf16x2_t); return __builtin_bit_cast(unsigned, b); }
;     if (ldk == 0) ldk = K;
;     const int c4 = lane & 15, kr = lane >> 4;
; #pragma unroll 8
;     for (int i = 0; i < 16; ++i) { const int kk = 4 * i + kr; const float gs = gain ? gain[k0 + kk] : 1.f; const f32x4 v = *(const f32x4*)(W + (size_t)(k0 + kk) * N + n0 + 4 * c4); *(LAS f32x4*)(scr + kk * 68 + 4 * c4) = v * gs; }
;     asm volatile("s_waitcnt lgkmcnt(0)" ::: "memory");
;     const int c = lane & 7;
; #pragma unroll
;     for (int j = 0; j < 8; ++j) { const int n = (lane >> 3) + 8 * j; const LAS float* s = scr + (8 * c) * 68 + n;
;         u32x4 o; o.x = pk2(s[0 * 68], s[1 * 68]); o.y = pk2(s[2 * 68], s[3 * 68]); o.z = pk2(s[4 * 68], s[5 * 68]); o.w = pk2(s[6 * 68], s[7 * 68]);
;         *(u32x4*)(WT + (size_t)(drow0 + n) * ldk + koff + k0 + 8 * c) = o; }
;     asm volatile("s_waitcnt lgkmcnt(0)" ::: "memory");
; }
;     const int nblk = N / 64, kb = item / nblk, nb = item % nblk;
;     transpose_item(W, N, K, WT, gain, nb * 64, kb * 64, nb * 64, scr, lane, ldk, koff);
.LBB0_423:
	v_lshl_add_u64 v[140:141], v[48:49], 0, s[42:43]
	global_load_dwordx4 v[140:143], v[140:141], off
	v_lshl_add_u64 v[144:145], v[46:47], 0, s[42:43]
	global_load_dwordx4 v[144:147], v[144:145], off
	v_lshl_add_u64 v[148:149], v[44:45], 0, s[42:43]
	global_load_dwordx4 v[148:151], v[148:149], off
	v_lshl_add_u64 v[152:153], v[42:43], 0, s[42:43]
	global_load_dwordx4 v[152:155], v[152:153], off
	v_lshl_add_u64 v[156:157], v[40:41], 0, s[42:43]
	global_load_dwordx4 v[156:159], v[156:157], off
	v_lshl_add_u64 v[160:161], v[38:39], 0, s[42:43]
	global_load_dwordx4 v[160:163], v[160:161], off
	v_lshl_add_u64 v[164:165], v[36:37], 0, s[42:43]
	global_load_dwordx4 v[164:167], v[164:165], off
	v_lshl_add_u64 v[168:169], v[34:35], 0, s[42:43]
	global_load_dwordx4 v[168:171], v[168:169], off
	s_add_u32 s42, s42, 0x20000
	s_addc_u32 s43, s43, 0
	v_lshl_add_u64 v[108:109], v[48:49], 0, s[42:43]
	global_load_dwordx4 v[108:111], v[108:109], off
	v_lshl_add_u64 v[112:113], v[46:47], 0, s[42:43]
	global_load_dwordx4 v[112:115], v[112:113], off
	v_lshl_add_u64 v[116:117], v[44:45], 0, s[42:43]
	global_load_dwordx4 v[116:119], v[116:117], off
	v_lshl_add_u64 v[120:121], v[42:43], 0, s[42:43]
	global_load_dwordx4 v[120:123], v[120:121], off
	v_lshl_add_u64 v[124:125], v[40:41], 0, s[42:43]
	global_load_dwordx4 v[124:127], v[124:125], off
	v_lshl_add_u64 v[240:241], v[38:39], 0, s[42:43]
	global_load_dwordx4 v[240:243], v[240:241], off
	v_lshl_add_u64 v[244:245], v[36:37], 0, s[42:43]
	global_load_dwordx4 v[244:247], v[244:245], off
	v_lshl_add_u64 v[248:249], v[34:35], 0, s[42:43]
	global_load_dwordx4 v[248:251], v[248:249], off
	s_add_u32 s42, s42, 0x20000
	s_addc_u32 s43, s43, 0
	s_waitcnt vmcnt(15)
	ds_write_b128 v33, v[140:143] offset:0
	s_waitcnt vmcnt(14)
	ds_write_b128 v33, v[144:147] offset:1088
	s_waitcnt vmcnt(13)
	ds_write_b128 v33, v[148:151] offset:2176
	s_waitcnt vmcnt(12)
	ds_write_b128 v33, v[152:155] offset:3264
	s_waitcnt vmcnt(11)
	ds_write_b128 v33, v[156:159] offset:4352
	s_waitcnt vmcnt(10)
	ds_write_b128 v33, v[160:163] offset:5440
	s_waitcnt vmcnt(9)
	ds_write_b128 v33, v[164:167] offset:6528
	s_waitcnt vmcnt(8)
	ds_write_b128 v33, v[168:171] offset:7616
	s_waitcnt vmcnt(7)
	ds_write_b128 v33, v[108:111] offset:8704
	s_waitcnt vmcnt(6)
	ds_write_b128 v33, v[112:115] offset:9792
	s_waitcnt vmcnt(5)
	ds_write_b128 v33, v[116:119] offset:10880
	s_waitcnt vmcnt(4)
	ds_write_b128 v33, v[120:123] offset:11968
	s_waitcnt vmcnt(3)
	ds_write_b128 v33, v[124:127] offset:13056
	s_waitcnt vmcnt(2)
	ds_write_b128 v33, v[240:243] offset:14144
	s_waitcnt vmcnt(1)
	ds_write_b128 v33, v[244:247] offset:15232
	s_waitcnt vmcnt(0)
	ds_write_b128 v33, v[248:251] offset:16320
	v_add_u32_e32 v33, 0x4400, v33
	s_cmp_lg_u32 s42, 0x40000
	s_waitcnt lgkmcnt(0)
	ds_read2_b32 v[40:41], v66 offset0:68 offset1:76
	ds_read2_b32 v[42:43], v66 offset1:8
	v_add_u32_e32 v58, 0x400, v66
	v_lshlrev_b16_e32 v33, 6, v1
	v_mov_b32_e32 v34, 0x3ea00
	ds_read2_b32 v[44:45], v66 offset0:136 offset1:144
	ds_read2_b32 v[46:47], v66 offset0:204 offset1:212
	ds_read2_b32 v[48:49], v58 offset0:16 offset1:24
	ds_read2_b32 v[50:51], v58 offset0:84 offset1:92
	ds_read2_b32 v[52:53], v58 offset0:152 offset1:160
	ds_read2_b32 v[54:55], v58 offset0:220 offset1:228
	v_and_b32_e32 v33, 0x3c0, v33
	v_lshl_add_u32 v34, v1, 2, v34
	v_and_b32_e32 v34, 0x3ffc0, v34
	s_waitcnt lgkmcnt(6)
	v_cvt_pk_bf16_f32 v36, v42, v40
	v_or_b32_sdwa v40, v3, v33 dst_sel:DWORD dst_unused:UNUSED_PAD src0_sel:DWORD src1_sel:WORD_0
	v_lshlrev_b32_e32 v34, 1, v34
	v_mov_b32_e32 v35, v2
	v_mul_u32_u24_e32 v40, 0xb00, v40
	v_lshl_add_u64 v[34:35], v[18:19], 0, v[34:35]
	v_lshlrev_b32_e32 v56, 1, v40
	v_mov_b32_e32 v57, v2
	v_or_b32_sdwa v40, v67, v33 dst_sel:DWORD dst_unused:UNUSED_PAD src0_sel:DWORD src1_sel:WORD_0
	s_waitcnt lgkmcnt(4)
	v_cvt_pk_bf16_f32 v37, v44, v46
	s_waitcnt lgkmcnt(2)
	v_cvt_pk_bf16_f32 v38, v48, v50
	s_waitcnt lgkmcnt(0)
; #define LAS __attribute__((address_space(3)))
; __device__ __forceinline__ unsigned pk2(float lo, float hi) { f32x2 v = {lo, hi}; bf16x2_t b = __builtin_convertvector(v, bf16x2_t); return __builtin_bit_cast(unsigned, b); }
;     ...
;     const int c = lane & 7;
; #pragma unroll
;     for (int j = 0; j < 8; ++j) { const int n = (lane >> 3) + 8 * j; const LAS float* s = scr + (8 * c) * 68 + n;
;         u32x4 o; o.x = pk2(s[0 * 68], s[1 * 68]); o.y = pk2(s[2 * 68], s[3 * 68]); o.z = pk2(s[4 * 68], s[5 * 68]); o.w = pk2(s[6 * 68], s[7 * 68]);
;         *(u32x4*)(WT + (size_t)(drow0 + n) * ldk + koff + k0 + 8 * c) = o; }
;     asm volatile("s_waitcnt lgkmcnt(0)" ::: "memory");
; }
	v_cvt_pk_bf16_f32 v39, v52, v54
	v_lshl_add_u64 v[56:57], v[34:35], 0, v[56:57]
	v_mul_u32_u24_e32 v40, 0xb00, v40
	global_store_dwordx4 v[56:57], v[36:39], off
	v_lshlrev_b32_e32 v40, 1, v40
	v_mov_b32_e32 v57, v2
	v_cvt_pk_bf16_f32 v36, v43, v41
	v_mov_b32_e32 v41, v2
	v_cvt_pk_bf16_f32 v37, v45, v47
	v_cvt_pk_bf16_f32 v38, v49, v51
	v_cvt_pk_bf16_f32 v39, v53, v55
	v_lshl_add_u64 v[40:41], v[34:35], 0, v[40:41]
	global_store_dwordx4 v[40:41], v[36:39], off
	ds_read2_b32 v[40:41], v66 offset0:16 offset1:24
	ds_read2_b32 v[42:43], v66 offset0:84 offset1:92
	ds_read2_b32 v[44:45], v66 offset0:152 offset1:160
	ds_read2_b32 v[46:47], v66 offset0:220 offset1:228
	ds_read2_b32 v[48:49], v58 offset0:32 offset1:40
	ds_read2_b32 v[50:51], v58 offset0:100 offset1:108
	ds_read2_b32 v[52:53], v58 offset0:168 offset1:176
	ds_read2_b32 v[54:55], v58 offset0:236 offset1:244
	s_waitcnt lgkmcnt(6)
	v_cvt_pk_bf16_f32 v36, v40, v42
	v_or_b32_sdwa v40, v68, v33 dst_sel:DWORD dst_unused:UNUSED_PAD src0_sel:DWORD src1_sel:WORD_0
	v_mul_u32_u24_e32 v40, 0xb00, v40
	v_lshlrev_b32_e32 v56, 1, v40
	v_or_b32_sdwa v40, v69, v33 dst_sel:DWORD dst_unused:UNUSED_PAD src0_sel:DWORD src1_sel:WORD_0
	s_waitcnt lgkmcnt(4)
	v_cvt_pk_bf16_f32 v37, v44, v46
	s_waitcnt lgkmcnt(2)
	v_cvt_pk_bf16_f32 v38, v48, v50
	s_waitcnt lgkmcnt(0)
	v_cvt_pk_bf16_f32 v39, v52, v54
	v_lshl_add_u64 v[56:57], v[34:35], 0, v[56:57]
	v_mul_u32_u24_e32 v40, 0xb00, v40
	global_store_dwordx4 v[56:57], v[36:39], off
	v_lshlrev_b32_e32 v40, 1, v40
	v_mov_b32_e32 v57, v2
	v_cvt_pk_bf16_f32 v36, v41, v43
	v_mov_b32_e32 v41, v2
	v_cvt_pk_bf16_f32 v37, v45, v47
	v_cvt_pk_bf16_f32 v38, v49, v51
	v_cvt_pk_bf16_f32 v39, v53, v55
	v_lshl_add_u64 v[40:41], v[34:35], 0, v[40:41]
	global_store_dwordx4 v[40:41], v[36:39], off
	ds_read2_b32 v[40:41], v66 offset0:32 offset1:40
	ds_read2_b32 v[42:43], v66 offset0:100 offset1:108
	v_add_u32_e32 v39, 0x600, v66
	ds_read2_b32 v[44:45], v66 offset0:168 offset1:176
	ds_read2_b32 v[46:47], v66 offset0:236 offset1:244
	ds_read2_b32 v[48:49], v58 offset0:48 offset1:56
	ds_read2_b32 v[50:51], v58 offset0:116 offset1:124
	ds_read2_b32 v[52:53], v58 offset0:184 offset1:192
	ds_read2_b32 v[54:55], v39 offset0:124 offset1:132
	s_waitcnt lgkmcnt(6)
	v_cvt_pk_bf16_f32 v36, v40, v42
	v_or_b32_sdwa v40, v70, v33 dst_sel:DWORD dst_unused:UNUSED_PAD src0_sel:DWORD src1_sel:WORD_0
	v_mul_u32_u24_e32 v40, 0xb00, v40
	v_lshlrev_b32_e32 v56, 1, v40
	v_or_b32_sdwa v40, v71, v33 dst_sel:DWORD dst_unused:UNUSED_PAD src0_sel:DWORD src1_sel:WORD_0
	s_waitcnt lgkmcnt(4)
	v_cvt_pk_bf16_f32 v37, v44, v46
	s_waitcnt lgkmcnt(2)
	v_cvt_pk_bf16_f32 v38, v48, v50
	s_waitcnt lgkmcnt(0)
	v_cvt_pk_bf16_f32 v39, v52, v54
	v_lshl_add_u64 v[56:57], v[34:35], 0, v[56:57]
	v_mul_u32_u24_e32 v40, 0xb00, v40
	global_store_dwordx4 v[56:57], v[36:39], off
	v_lshlrev_b32_e32 v40, 1, v40
	v_mov_b32_e32 v57, v2
	v_cvt_pk_bf16_f32 v36, v41, v43
	v_mov_b32_e32 v41, v2
	v_cvt_pk_bf16_f32 v37, v45, v47
	v_cvt_pk_bf16_f32 v38, v49, v51
	v_cvt_pk_bf16_f32 v39, v53, v55
	v_lshl_add_u64 v[40:41], v[34:35], 0, v[40:41]
	global_store_dwordx4 v[40:41], v[36:39], off
	ds_read2_b32 v[40:41], v66 offset0:48 offset1:56
	ds_read2_b32 v[42:43], v66 offset0:116 offset1:124
	v_add_u32_e32 v37, 0x200, v66
	v_add_u32_e32 v39, 0x800, v66
	ds_read2_b32 v[44:45], v66 offset0:184 offset1:192
	ds_read2_b32 v[46:47], v37 offset0:124 offset1:132
	ds_read2_b32 v[48:49], v58 offset0:64 offset1:72
	ds_read2_b32 v[50:51], v58 offset0:132 offset1:140
	ds_read2_b32 v[52:53], v58 offset0:200 offset1:208
	ds_read2_b32 v[54:55], v39 offset0:12 offset1:20
	s_waitcnt lgkmcnt(6)
	v_cvt_pk_bf16_f32 v36, v40, v42
	v_or_b32_sdwa v40, v72, v33 dst_sel:DWORD dst_unused:UNUSED_PAD src0_sel:DWORD src1_sel:WORD_0
	v_mul_u32_u24_e32 v40, 0xb00, v40
	v_lshlrev_b32_e32 v56, 1, v40
	v_or_b32_sdwa v33, v73, v33 dst_sel:DWORD dst_unused:UNUSED_PAD src0_sel:DWORD src1_sel:WORD_0
	s_waitcnt lgkmcnt(4)
	v_cvt_pk_bf16_f32 v37, v44, v46
	s_waitcnt lgkmcnt(2)
	v_cvt_pk_bf16_f32 v38, v48, v50
	s_waitcnt lgkmcnt(0)
	v_cvt_pk_bf16_f32 v39, v52, v54
	v_lshl_add_u64 v[56:57], v[34:35], 0, v[56:57]
	v_mul_u32_u24_e32 v33, 0xb00, v33
	global_store_dwordx4 v[56:57], v[36:39], off
	v_lshlrev_b32_e32 v40, 1, v33
	s_nop 0
	v_cvt_pk_bf16_f32 v36, v41, v43
	v_mov_b32_e32 v41, v2
	v_cvt_pk_bf16_f32 v37, v45, v47
	v_cvt_pk_bf16_f32 v38, v49, v51
	v_cvt_pk_bf16_f32 v39, v53, v55
	v_lshl_add_u64 v[34:35], v[34:35], 0, v[40:41]
	global_store_dwordx4 v[34:35], v[36:39], off
	s_waitcnt lgkmcnt(0)

; #define LAS __attribute__((address_space(3)))
;     if (ldk == 0) ldk = K;
;     const int c4 = lane & 15, kr = lane >> 4;
; #pragma unroll 8
;     for (int i = 0; i < 16; ++i) { const int kk = 4 * i + kr; const float gs = gain ? gain[k0 + kk] : 1.f; const f32x4 v = *(const f32x4*)(W + (size_t)(k0 + kk) * N + n0 + 4 * c4); *(LAS f32x4*)(scr + kk * 68 + 4 * c4) = v * gs; }
;     asm volatile("s_waitcnt lgkmcnt(0)" ::: "memory");
; __device__ __forceinline__ void tr_gu(const float* W, bf16_t* WT, const float* gain, int up, int item, LAS float* scr, int lane) {
;     const int nblk = DFF / 64, kb = item / nblk, nb = item % nblk, n0 = nb * 64;
;     transpose_item(W, DFF, DM, WT, gain, (n0 >> 7) * 256 + (n0 & 127) + up * 128, kb * 64, n0, scr, lane);
; }
.LBB0_429:
	v_cndmask_b32_e64 v126, 0, 1, s[56:57]
	v_mov_b32_e32 v106, 1.0
	v_mov_b32_e32 v108, 1.0
	v_mov_b32_e32 v110, 1.0
	v_mov_b32_e32 v112, 1.0
	v_mov_b32_e32 v114, 1.0
	v_mov_b32_e32 v116, 1.0
	v_mov_b32_e32 v118, 1.0
	v_mov_b32_e32 v120, 1.0
	v_cmp_ne_u32_e64 s[40:41], 1, v126
	s_andn2_b64 vcc, exec, s[56:57]
	s_cbranch_vccnz .Lpw_ng_429
	v_lshl_add_u64 v[122:123], v[52:53], 0, s[46:47]
	global_load_dword v106, v[122:123], off
	v_lshl_add_u64 v[124:125], v[36:37], 0, s[46:47]
	global_load_dword v108, v[124:125], off offset:16
	global_load_dword v110, v[124:125], off offset:32
	global_load_dword v112, v[124:125], off offset:48
	global_load_dword v114, v[124:125], off offset:64
	global_load_dword v116, v[124:125], off offset:80
	global_load_dword v118, v[124:125], off offset:96
	global_load_dword v120, v[124:125], off offset:112
.Lpw_ng_429:
	v_lshl_add_u64 v[140:141], v[50:51], 0, s[54:55]
	global_load_dwordx4 v[140:143], v[140:141], off
	v_lshl_add_u64 v[144:145], v[48:49], 0, s[54:55]
	global_load_dwordx4 v[144:147], v[144:145], off
	v_lshl_add_u64 v[148:149], v[46:47], 0, s[54:55]
	global_load_dwordx4 v[148:151], v[148:149], off
	v_lshl_add_u64 v[152:153], v[44:45], 0, s[54:55]
	global_load_dwordx4 v[152:155], v[152:153], off
	v_lshl_add_u64 v[156:157], v[42:43], 0, s[54:55]
	global_load_dwordx4 v[156:159], v[156:157], off
	v_lshl_add_u64 v[160:161], v[40:41], 0, s[54:55]
	global_load_dwordx4 v[160:163], v[160:161], off
	v_lshl_add_u64 v[164:165], v[38:39], 0, s[54:55]
	global_load_dwordx4 v[164:167], v[164:165], off
	v_lshl_add_u64 v[168:169], v[34:35], 0, s[54:55]
	global_load_dwordx4 v[168:171], v[168:169], off
	s_add_u32 s54, s54, 0x58000
	s_addc_u32 s55, s55, 0
	v_lshl_add_u64 v[36:37], v[36:37], 0, s[34:35]
	v_lshl_add_u64 v[52:53], v[52:53], 0, s[34:35]
	s_waitcnt vmcnt(7)
	v_pk_mul_f32 v[140:141], v[140:141], v[106:107] op_sel_hi:[1,0]
	v_pk_mul_f32 v[142:143], v[142:143], v[106:107] op_sel_hi:[1,0]
	ds_write_b128 v60, v[140:143] offset:0
	s_waitcnt vmcnt(6)
	v_pk_mul_f32 v[144:145], v[144:145], v[108:109] op_sel_hi:[1,0]
	v_pk_mul_f32 v[146:147], v[146:147], v[108:109] op_sel_hi:[1,0]
	ds_write_b128 v60, v[144:147] offset:1088
	s_waitcnt vmcnt(5)
	v_pk_mul_f32 v[148:149], v[148:149], v[110:111] op_sel_hi:[1,0]
	v_pk_mul_f32 v[150:151], v[150:151], v[110:111] op_sel_hi:[1,0]
	ds_write_b128 v60, v[148:151] offset:2176
	s_waitcnt vmcnt(4)
	v_pk_mul_f32 v[152:153], v[152:153], v[112:113] op_sel_hi:[1,0]
	v_pk_mul_f32 v[154:155], v[154:155], v[112:113] op_sel_hi:[1,0]
	ds_write_b128 v60, v[152:155] offset:3264
	s_waitcnt vmcnt(3)
	v_pk_mul_f32 v[156:157], v[156:157], v[114:115] op_sel_hi:[1,0]
	v_pk_mul_f32 v[158:159], v[158:159], v[114:115] op_sel_hi:[1,0]
	ds_write_b128 v60, v[156:159] offset:4352
	s_waitcnt vmcnt(2)
	v_pk_mul_f32 v[160:161], v[160:161], v[116:117] op_sel_hi:[1,0]
	v_pk_mul_f32 v[162:163], v[162:163], v[116:117] op_sel_hi:[1,0]
	ds_write_b128 v60, v[160:163] offset:5440
	s_waitcnt vmcnt(1)
	v_pk_mul_f32 v[164:165], v[164:165], v[118:119] op_sel_hi:[1,0]
	v_pk_mul_f32 v[166:167], v[166:167], v[118:119] op_sel_hi:[1,0]
	ds_write_b128 v60, v[164:167] offset:6528
	s_waitcnt vmcnt(0)
	v_pk_mul_f32 v[168:169], v[168:169], v[120:121] op_sel_hi:[1,0]
	v_pk_mul_f32 v[170:171], v[170:171], v[120:121] op_sel_hi:[1,0]
	ds_write_b128 v60, v[168:171] offset:7616
	v_add_u32_e32 v60, 0x2200, v60
	s_cmp_lg_u32 s54, 0xb0000
	s_cbranch_scc1 .LBB0_429
	s_branch .LBB0_445

; #define LAS __attribute__((address_space(3)))
;     if (ldk == 0) ldk = K;
;     const int c4 = lane & 15, kr = lane >> 4;
; #pragma unroll 8
;     for (int i = 0; i < 16; ++i) { const int kk = 4 * i + kr; const float gs = gain ? gain[k0 + kk] : 1.f; const f32x4 v = *(const f32x4*)(W + (size_t)(k0 + kk) * N + n0 + 4 * c4); *(LAS f32x4*)(scr + kk * 68 + 4 * c4) = v * gs; }
;     asm volatile("s_waitcnt lgkmcnt(0)" ::: "memory");
.LBB0_450:
	v_add_u32_e32 v44, s14, v40
	v_cndmask_b32_e64 v126, 0, 1, s[54:55]
	v_ashrrev_i32_e32 v45, 31, v44
	v_mov_b32_e32 v106, 1.0
	v_mov_b32_e32 v108, 1.0
	v_mov_b32_e32 v110, 1.0
	v_mov_b32_e32 v112, 1.0
	v_mov_b32_e32 v114, 1.0
	v_mov_b32_e32 v116, 1.0
	v_mov_b32_e32 v118, 1.0
	v_mov_b32_e32 v120, 1.0
	v_cmp_ne_u32_e64 s[40:41], 1, v126
	s_andn2_b64 vcc, exec, s[54:55]
	s_cbranch_vccnz .Lpw_ng_450
	v_lshl_add_u64 v[122:123], v[44:45], 2, s[52:53]
	global_load_dword v106, v[122:123], off
	global_load_dword v108, v[42:43], off offset:-96
	global_load_dword v110, v[42:43], off offset:-80
	global_load_dword v112, v[42:43], off offset:-64
	global_load_dword v114, v[42:43], off offset:-48
	global_load_dword v116, v[42:43], off offset:-32
	global_load_dword v118, v[42:43], off offset:-16
	global_load_dword v120, v[42:43], off
.Lpw_ng_450:
	v_mad_i64_i32 v[140:141], s[56:57], v44, s66, v[38:39]
	global_load_dwordx4 v[140:143], v[140:141], off
	v_add_u32_e32 v126, 4, v44
	v_mad_i64_i32 v[144:145], s[56:57], v126, s66, v[38:39]
	global_load_dwordx4 v[144:147], v[144:145], off
	v_add_u32_e32 v126, 8, v44
	v_mad_i64_i32 v[148:149], s[56:57], v126, s66, v[38:39]
	global_load_dwordx4 v[148:151], v[148:149], off
	v_add_u32_e32 v126, 12, v44
	v_mad_i64_i32 v[152:153], s[56:57], v126, s66, v[38:39]
	global_load_dwordx4 v[152:155], v[152:153], off
	v_add_u32_e32 v126, 16, v44
	v_mad_i64_i32 v[156:157], s[56:57], v126, s66, v[38:39]
	global_load_dwordx4 v[156:159], v[156:157], off
	v_add_u32_e32 v126, 20, v44
	v_mad_i64_i32 v[160:161], s[56:57], v126, s66, v[38:39]
	global_load_dwordx4 v[160:163], v[160:161], off
	v_add_u32_e32 v126, 24, v44
	v_mad_i64_i32 v[164:165], s[56:57], v126, s66, v[38:39]
	global_load_dwordx4 v[164:167], v[164:165], off
	v_add_u32_e32 v126, 28, v44
	v_mad_i64_i32 v[168:169], s[56:57], v126, s66, v[38:39]
	global_load_dwordx4 v[168:171], v[168:169], off
	s_add_i32 s14, s14, 32
	v_lshl_add_u64 v[42:43], v[42:43], 0, s[34:35]
	s_waitcnt vmcnt(7)
	v_pk_mul_f32 v[140:141], v[140:141], v[106:107] op_sel_hi:[1,0]
	v_pk_mul_f32 v[142:143], v[142:143], v[106:107] op_sel_hi:[1,0]
	ds_write_b128 v33, v[140:143] offset:0
	s_waitcnt vmcnt(6)
	v_pk_mul_f32 v[144:145], v[144:145], v[108:109] op_sel_hi:[1,0]
	v_pk_mul_f32 v[146:147], v[146:147], v[108:109] op_sel_hi:[1,0]
	ds_write_b128 v33, v[144:147] offset:1088
	s_waitcnt vmcnt(5)
	v_pk_mul_f32 v[148:149], v[148:149], v[110:111] op_sel_hi:[1,0]
	v_pk_mul_f32 v[150:151], v[150:151], v[110:111] op_sel_hi:[1,0]
	ds_write_b128 v33, v[148:151] offset:2176
	s_waitcnt vmcnt(4)
	v_pk_mul_f32 v[152:153], v[152:153], v[112:113] op_sel_hi:[1,0]
	v_pk_mul_f32 v[154:155], v[154:155], v[112:113] op_sel_hi:[1,0]
	ds_write_b128 v33, v[152:155] offset:3264
	s_waitcnt vmcnt(3)
	v_pk_mul_f32 v[156:157], v[156:157], v[114:115] op_sel_hi:[1,0]
	v_pk_mul_f32 v[158:159], v[158:159], v[114:115] op_sel_hi:[1,0]
	ds_write_b128 v33, v[156:159] offset:4352
	s_waitcnt vmcnt(2)
	v_pk_mul_f32 v[160:161], v[160:161], v[116:117] op_sel_hi:[1,0]
	v_pk_mul_f32 v[162:163], v[162:163], v[116:117] op_sel_hi:[1,0]
	ds_write_b128 v33, v[160:163] offset:5440
	s_waitcnt vmcnt(1)
	v_pk_mul_f32 v[164:165], v[164:165], v[118:119] op_sel_hi:[1,0]
	v_pk_mul_f32 v[166:167], v[166:167], v[118:119] op_sel_hi:[1,0]
	ds_write_b128 v33, v[164:167] offset:6528
	s_waitcnt vmcnt(0)
	v_pk_mul_f32 v[168:169], v[168:169], v[120:121] op_sel_hi:[1,0]
	v_pk_mul_f32 v[170:171], v[170:171], v[120:121] op_sel_hi:[1,0]
	ds_write_b128 v33, v[168:171] offset:7616
	v_add_u32_e32 v33, 0x2200, v33
	s_cmp_lg_u32 s14, 64
	s_cbranch_scc1 .LBB0_450
	s_branch .LBB0_323

; #define LAS __attribute__((address_space(3)))
;     if (ldk == 0) ldk = K;
;     const int c4 = lane & 15, kr = lane >> 4;
; #pragma unroll 8
;     for (int i = 0; i < 16; ++i) { const int kk = 4 * i + kr; const float gs = gain ? gain[k0 + kk] : 1.f; const f32x4 v = *(const f32x4*)(W + (size_t)(k0 + kk) * N + n0 + 4 * c4); *(LAS f32x4*)(scr + kk * 68 + 4 * c4) = v * gs; }
;     asm volatile("s_waitcnt lgkmcnt(0)" ::: "memory");
;     const int nblk = N / 64, kb = item / nblk, nb = item % nblk;
;     transpose_item(W, N, K, WT, gain, nb * 64, kb * 64, nb * 64, scr, lane, ldk, koff);
; }
.LBB0_477:
	v_cndmask_b32_e64 v126, 0, 1, s[70:71]
	v_mov_b32_e32 v106, 1.0
	v_mov_b32_e32 v108, 1.0
	v_mov_b32_e32 v110, 1.0
	v_mov_b32_e32 v112, 1.0
	v_mov_b32_e32 v114, 1.0
	v_mov_b32_e32 v116, 1.0
	v_mov_b32_e32 v118, 1.0
	v_mov_b32_e32 v120, 1.0
	v_cmp_ne_u32_e64 s[40:41], 1, v126
	s_andn2_b64 vcc, exec, s[70:71]
	s_cbranch_vccnz .Lpw_ng_477
	v_lshl_add_u64 v[122:123], v[38:39], 0, s[50:51]
	global_load_dword v106, v[122:123], off
	v_lshl_add_u64 v[124:125], v[22:23], 0, s[50:51]
	global_load_dword v108, v[124:125], off offset:16
	global_load_dword v110, v[124:125], off offset:32
	global_load_dword v112, v[124:125], off offset:48
	global_load_dword v114, v[124:125], off offset:64
	global_load_dword v116, v[124:125], off offset:80
	global_load_dword v118, v[124:125], off offset:96
	global_load_dword v120, v[124:125], off offset:112
.Lpw_ng_477:
	v_lshl_add_u64 v[140:141], v[36:37], 0, s[68:69]
	global_load_dwordx4 v[140:143], v[140:141], off
	v_lshl_add_u64 v[144:145], v[34:35], 0, s[68:69]
	global_load_dwordx4 v[144:147], v[144:145], off
	v_lshl_add_u64 v[148:149], v[32:33], 0, s[68:69]
	global_load_dwordx4 v[148:151], v[148:149], off
	v_lshl_add_u64 v[152:153], v[30:31], 0, s[68:69]
	global_load_dwordx4 v[152:155], v[152:153], off
	v_lshl_add_u64 v[156:157], v[28:29], 0, s[68:69]
	global_load_dwordx4 v[156:159], v[156:157], off
	v_lshl_add_u64 v[160:161], v[26:27], 0, s[68:69]
	global_load_dwordx4 v[160:163], v[160:161], off
	v_lshl_add_u64 v[164:165], v[24:25], 0, s[68:69]
	global_load_dwordx4 v[164:167], v[164:165], off
	v_lshl_add_u64 v[168:169], v[20:21], 0, s[68:69]
	global_load_dwordx4 v[168:171], v[168:169], off
	s_add_u32 s68, s68, 0x110000
	s_addc_u32 s69, s69, 0
	v_lshl_add_u64 v[22:23], v[22:23], 0, s[34:35]
	v_lshl_add_u64 v[38:39], v[38:39], 0, s[34:35]
	s_waitcnt vmcnt(7)
	v_pk_mul_f32 v[140:141], v[140:141], v[106:107] op_sel_hi:[1,0]
	v_pk_mul_f32 v[142:143], v[142:143], v[106:107] op_sel_hi:[1,0]
	ds_write_b128 v64, v[140:143] offset:0
	s_waitcnt vmcnt(6)
	v_pk_mul_f32 v[144:145], v[144:145], v[108:109] op_sel_hi:[1,0]
	v_pk_mul_f32 v[146:147], v[146:147], v[108:109] op_sel_hi:[1,0]
	ds_write_b128 v64, v[144:147] offset:1088
	s_waitcnt vmcnt(5)
	v_pk_mul_f32 v[148:149], v[148:149], v[110:111] op_sel_hi:[1,0]
	v_pk_mul_f32 v[150:151], v[150:151], v[110:111] op_sel_hi:[1,0]
	ds_write_b128 v64, v[148:151] offset:2176
	s_waitcnt vmcnt(4)
	v_pk_mul_f32 v[152:153], v[152:153], v[112:113] op_sel_hi:[1,0]
	v_pk_mul_f32 v[154:155], v[154:155], v[112:113] op_sel_hi:[1,0]
	ds_write_b128 v64, v[152:155] offset:3264
	s_waitcnt vmcnt(3)
	v_pk_mul_f32 v[156:157], v[156:157], v[114:115] op_sel_hi:[1,0]
	v_pk_mul_f32 v[158:159], v[158:159], v[114:115] op_sel_hi:[1,0]
	ds_write_b128 v64, v[156:159] offset:4352
	s_waitcnt vmcnt(2)
	v_pk_mul_f32 v[160:161], v[160:161], v[116:117] op_sel_hi:[1,0]
	v_pk_mul_f32 v[162:163], v[162:163], v[116:117] op_sel_hi:[1,0]
	ds_write_b128 v64, v[160:163] offset:5440
	s_waitcnt vmcnt(1)
	v_pk_mul_f32 v[164:165], v[164:165], v[118:119] op_sel_hi:[1,0]
	v_pk_mul_f32 v[166:167], v[166:167], v[118:119] op_sel_hi:[1,0]
	ds_write_b128 v64, v[164:167] offset:6528
	s_waitcnt vmcnt(0)
	v_pk_mul_f32 v[168:169], v[168:169], v[120:121] op_sel_hi:[1,0]
	v_pk_mul_f32 v[170:171], v[170:171], v[120:121] op_sel_hi:[1,0]
	ds_write_b128 v64, v[168:171] offset:7616
	v_add_u32_e32 v64, 0x2200, v64
	s_cmp_lg_u32 s68, 0x220000
	s_cbranch_scc1 .LBB0_477
	s_branch .LBB0_493

; #define LAS __attribute__((address_space(3)))
;     if (ldk == 0) ldk = K;
;     const int c4 = lane & 15, kr = lane >> 4;
; #pragma unroll 8
;     for (int i = 0; i < 16; ++i) { const int kk = 4 * i + kr; const float gs = gain ? gain[k0 + kk] : 1.f; const f32x4 v = *(const f32x4*)(W + (size_t)(k0 + kk) * N + n0 + 4 * c4); *(LAS f32x4*)(scr + kk * 68 + 4 * c4) = v * gs; }
;     asm volatile("s_waitcnt lgkmcnt(0)" ::: "memory");
; __device__ __forceinline__ void tr_gu(const float* W, bf16_t* WT, const float* gain, int up, int item, LAS float* scr, int lane) {
;     const int nblk = DFF / 64, kb = item / nblk, nb = item % nblk, n0 = nb * 64;
;     transpose_item(W, DFF, DM, WT, gain, (n0 >> 7) * 256 + (n0 & 127) + up * 128, kb * 64, n0, scr, lane);
; }
.LBB0_502:
	v_cndmask_b32_e64 v126, 0, 1, s[58:59]
	v_mov_b32_e32 v106, 1.0
	v_mov_b32_e32 v108, 1.0
	v_mov_b32_e32 v110, 1.0
	v_mov_b32_e32 v112, 1.0
	v_mov_b32_e32 v114, 1.0
	v_mov_b32_e32 v116, 1.0
	v_mov_b32_e32 v118, 1.0
	v_mov_b32_e32 v120, 1.0
	v_cmp_ne_u32_e64 s[40:41], 1, v126
	s_andn2_b64 vcc, exec, s[58:59]
	s_cbranch_vccnz .Lpw_ng_502
	v_lshl_add_u64 v[122:123], v[38:39], 0, s[50:51]
	global_load_dword v106, v[122:123], off
	v_lshl_add_u64 v[124:125], v[22:23], 0, s[50:51]
	global_load_dword v108, v[124:125], off offset:16
	global_load_dword v110, v[124:125], off offset:32
	global_load_dword v112, v[124:125], off offset:48
	global_load_dword v114, v[124:125], off offset:64
	global_load_dword v116, v[124:125], off offset:80
	global_load_dword v118, v[124:125], off offset:96
	global_load_dword v120, v[124:125], off offset:112
.Lpw_ng_502:
	v_lshl_add_u64 v[140:141], v[36:37], 0, s[56:57]
	global_load_dwordx4 v[140:143], v[140:141], off
	v_lshl_add_u64 v[144:145], v[34:35], 0, s[56:57]
	global_load_dwordx4 v[144:147], v[144:145], off
	v_lshl_add_u64 v[148:149], v[32:33], 0, s[56:57]
	global_load_dwordx4 v[148:151], v[148:149], off
	v_lshl_add_u64 v[152:153], v[30:31], 0, s[56:57]
	global_load_dwordx4 v[152:155], v[152:153], off
	v_lshl_add_u64 v[156:157], v[28:29], 0, s[56:57]
	global_load_dwordx4 v[156:159], v[156:157], off
	v_lshl_add_u64 v[160:161], v[26:27], 0, s[56:57]
	global_load_dwordx4 v[160:163], v[160:161], off
	v_lshl_add_u64 v[164:165], v[24:25], 0, s[56:57]
	global_load_dwordx4 v[164:167], v[164:165], off
	v_lshl_add_u64 v[168:169], v[20:21], 0, s[56:57]
	global_load_dwordx4 v[168:171], v[168:169], off
	s_add_u32 s56, s56, 0x58000
	s_addc_u32 s57, s57, 0
	v_lshl_add_u64 v[22:23], v[22:23], 0, s[34:35]
	v_lshl_add_u64 v[38:39], v[38:39], 0, s[34:35]
	s_waitcnt vmcnt(7)
	v_pk_mul_f32 v[140:141], v[140:141], v[106:107] op_sel_hi:[1,0]
	v_pk_mul_f32 v[142:143], v[142:143], v[106:107] op_sel_hi:[1,0]
	ds_write_b128 v65, v[140:143] offset:0
	s_waitcnt vmcnt(6)
	v_pk_mul_f32 v[144:145], v[144:145], v[108:109] op_sel_hi:[1,0]
	v_pk_mul_f32 v[146:147], v[146:147], v[108:109] op_sel_hi:[1,0]
	ds_write_b128 v65, v[144:147] offset:1088
	s_waitcnt vmcnt(5)
	v_pk_mul_f32 v[148:149], v[148:149], v[110:111] op_sel_hi:[1,0]
	v_pk_mul_f32 v[150:151], v[150:151], v[110:111] op_sel_hi:[1,0]
	ds_write_b128 v65, v[148:151] offset:2176
	s_waitcnt vmcnt(4)
	v_pk_mul_f32 v[152:153], v[152:153], v[112:113] op_sel_hi:[1,0]
	v_pk_mul_f32 v[154:155], v[154:155], v[112:113] op_sel_hi:[1,0]
	ds_write_b128 v65, v[152:155] offset:3264
	s_waitcnt vmcnt(3)
	v_pk_mul_f32 v[156:157], v[156:157], v[114:115] op_sel_hi:[1,0]
	v_pk_mul_f32 v[158:159], v[158:159], v[114:115] op_sel_hi:[1,0]
	ds_write_b128 v65, v[156:159] offset:4352
	s_waitcnt vmcnt(2)
	v_pk_mul_f32 v[160:161], v[160:161], v[116:117] op_sel_hi:[1,0]
	v_pk_mul_f32 v[162:163], v[162:163], v[116:117] op_sel_hi:[1,0]
	ds_write_b128 v65, v[160:163] offset:5440
	s_waitcnt vmcnt(1)
	v_pk_mul_f32 v[164:165], v[164:165], v[118:119] op_sel_hi:[1,0]
	v_pk_mul_f32 v[166:167], v[166:167], v[118:119] op_sel_hi:[1,0]
	ds_write_b128 v65, v[164:167] offset:6528
	s_waitcnt vmcnt(0)
	v_pk_mul_f32 v[168:169], v[168:169], v[120:121] op_sel_hi:[1,0]
	v_pk_mul_f32 v[170:171], v[170:171], v[120:121] op_sel_hi:[1,0]
	ds_write_b128 v65, v[168:171] offset:7616
	v_add_u32_e32 v65, 0x2200, v65
	s_cmp_lg_u32 s56, 0xb0000
	s_cbranch_scc1 .LBB0_502
	s_branch .LBB0_518

; #define LAS __attribute__((address_space(3)))
;     if (ldk == 0) ldk = K;
;     const int c4 = lane & 15, kr = lane >> 4;
; #pragma unroll 8
;     for (int i = 0; i < 16; ++i) { const int kk = 4 * i + kr; const float gs = gain ? gain[k0 + kk] : 1.f; const f32x4 v = *(const f32x4*)(W + (size_t)(k0 + kk) * N + n0 + 4 * c4); *(LAS f32x4*)(scr + kk * 68 + 4 * c4) = v * gs; }
;     asm volatile("s_waitcnt lgkmcnt(0)" ::: "memory");
.LBB0_523:
	v_add_u32_e32 v30, s30, v26
	v_cndmask_b32_e64 v126, 0, 1, s[56:57]
	v_ashrrev_i32_e32 v31, 31, v30
	v_mov_b32_e32 v106, 1.0
	v_mov_b32_e32 v108, 1.0
	v_mov_b32_e32 v110, 1.0
	v_mov_b32_e32 v112, 1.0
	v_mov_b32_e32 v114, 1.0
	v_mov_b32_e32 v116, 1.0
	v_mov_b32_e32 v118, 1.0
	v_mov_b32_e32 v120, 1.0
	v_cmp_ne_u32_e64 s[40:41], 1, v126
	s_andn2_b64 vcc, exec, s[56:57]
	s_cbranch_vccnz .Lpw_ng_523
	v_lshl_add_u64 v[122:123], v[30:31], 2, s[54:55]
	global_load_dword v106, v[122:123], off
	global_load_dword v108, v[28:29], off offset:-96
	global_load_dword v110, v[28:29], off offset:-80
	global_load_dword v112, v[28:29], off offset:-64
	global_load_dword v114, v[28:29], off offset:-48
	global_load_dword v116, v[28:29], off offset:-32
	global_load_dword v118, v[28:29], off offset:-16
	global_load_dword v120, v[28:29], off
.Lpw_ng_523:
	v_mad_i64_i32 v[140:141], s[58:59], v30, s66, v[24:25]
	global_load_dwordx4 v[140:143], v[140:141], off
	v_add_u32_e32 v126, 4, v30
	v_mad_i64_i32 v[144:145], s[58:59], v126, s66, v[24:25]
	global_load_dwordx4 v[144:147], v[144:145], off
	v_add_u32_e32 v126, 8, v30
	v_mad_i64_i32 v[148:149], s[58:59], v126, s66, v[24:25]
	global_load_dwordx4 v[148:151], v[148:149], off
	v_add_u32_e32 v126, 12, v30
	v_mad_i64_i32 v[152:153], s[58:59], v126, s66, v[24:25]
	global_load_dwordx4 v[152:155], v[152:153], off
	v_add_u32_e32 v126, 16, v30
	v_mad_i64_i32 v[156:157], s[58:59], v126, s66, v[24:25]
	global_load_dwordx4 v[156:159], v[156:157], off
	v_add_u32_e32 v126, 20, v30
	v_mad_i64_i32 v[160:161], s[58:59], v126, s66, v[24:25]
	global_load_dwordx4 v[160:163], v[160:161], off
	v_add_u32_e32 v126, 24, v30
	v_mad_i64_i32 v[164:165], s[58:59], v126, s66, v[24:25]
	global_load_dwordx4 v[164:167], v[164:165], off
	v_add_u32_e32 v126, 28, v30
	v_mad_i64_i32 v[168:169], s[58:59], v126, s66, v[24:25]
	global_load_dwordx4 v[168:171], v[168:169], off
	s_add_i32 s30, s30, 32
	v_lshl_add_u64 v[28:29], v[28:29], 0, s[34:35]
	s_waitcnt vmcnt(7)
	v_pk_mul_f32 v[140:141], v[140:141], v[106:107] op_sel_hi:[1,0]
	v_pk_mul_f32 v[142:143], v[142:143], v[106:107] op_sel_hi:[1,0]
	ds_write_b128 v19, v[140:143] offset:0
	s_waitcnt vmcnt(6)
	v_pk_mul_f32 v[144:145], v[144:145], v[108:109] op_sel_hi:[1,0]
	v_pk_mul_f32 v[146:147], v[146:147], v[108:109] op_sel_hi:[1,0]
	ds_write_b128 v19, v[144:147] offset:1088
	s_waitcnt vmcnt(5)
	v_pk_mul_f32 v[148:149], v[148:149], v[110:111] op_sel_hi:[1,0]
	v_pk_mul_f32 v[150:151], v[150:151], v[110:111] op_sel_hi:[1,0]
	ds_write_b128 v19, v[148:151] offset:2176
	s_waitcnt vmcnt(4)
	v_pk_mul_f32 v[152:153], v[152:153], v[112:113] op_sel_hi:[1,0]
	v_pk_mul_f32 v[154:155], v[154:155], v[112:113] op_sel_hi:[1,0]
	ds_write_b128 v19, v[152:155] offset:3264
	s_waitcnt vmcnt(3)
	v_pk_mul_f32 v[156:157], v[156:157], v[114:115] op_sel_hi:[1,0]
	v_pk_mul_f32 v[158:159], v[158:159], v[114:115] op_sel_hi:[1,0]
	ds_write_b128 v19, v[156:159] offset:4352
	s_waitcnt vmcnt(2)
	v_pk_mul_f32 v[160:161], v[160:161], v[116:117] op_sel_hi:[1,0]
	v_pk_mul_f32 v[162:163], v[162:163], v[116:117] op_sel_hi:[1,0]
	ds_write_b128 v19, v[160:163] offset:5440
	s_waitcnt vmcnt(1)
	v_pk_mul_f32 v[164:165], v[164:165], v[118:119] op_sel_hi:[1,0]
	v_pk_mul_f32 v[166:167], v[166:167], v[118:119] op_sel_hi:[1,0]
	ds_write_b128 v19, v[164:167] offset:6528
	s_waitcnt vmcnt(0)
	v_pk_mul_f32 v[168:169], v[168:169], v[120:121] op_sel_hi:[1,0]
	v_pk_mul_f32 v[170:171], v[170:171], v[120:121] op_sel_hi:[1,0]
	ds_write_b128 v19, v[168:171] offset:7616
	v_add_u32_e32 v19, 0x2200, v19
	s_cmp_lg_u32 s30, 64
	s_cbranch_scc1 .LBB0_523
	s_branch .LBB0_470
